# prio3 + merged waits + LDS read addresses of the B buffers from one hoisted VGPR with immediate offsets (no per-iteration VALU adds)
# speedup vs baseline: 1.0099x; 1.0033x over previous
; #define PG8_STAGE(bufoff, gbase, voff) do { _Pragma("unroll") for (int _i = 0; _i < 2; ++_i) \
;         __builtin_amdgcn_global_load_lds((const unsigned*)((const char*)(gbase) + (voff)[_i]), (PG8_LAS unsigned*)(lds + (bufoff) + ldsw + _i * 8192), 16, 0, 0); } while (0)
; #define PG8_LDA(dst, b, h) do { _Pragma("unroll") for (int m = 0; m < 4; ++m) _Pragma("unroll") for (int k = 0; k < 2; ++k) dst[m][k] = *(const PG8_LAS bf16x8*)(lds + PG8_SA(b, h) + aoff + m * 2048 + k * 1024); } while (0)
; #define PG8_LDB(dst, b, h) do { _Pragma("unroll") for (int n = 0; n < 2; ++n) _Pragma("unroll") for (int k = 0; k < 2; ++k) dst[n][k] = *(const PG8_LAS bf16x8*)(lds + PG8_SB(b, h) + boff + n * 2048 + k * 1024); } while (0)
; #define PG8_MMA(ai, bj, At, Bt) do { __builtin_amdgcn_s_setprio(1); _Pragma("unroll") for (int m = 0; m < 4; ++m) _Pragma("unroll") for (int n = 0; n < 2; ++n) _Pragma("unroll") for (int k = 0; k < 2; ++k) \
;         acc[ai][bj][m][n] = __builtin_amdgcn_mfma_f32_16x16x32_bf16(Bt[n][k], At[m][k], acc[ai][bj][m][n], 0, 0, 0); __builtin_amdgcn_s_setprio(0); } while (0)
; #define PG8_WAIT_V(n) asm volatile("s_waitcnt vmcnt(" #n ")" ::: "memory")
; #define PG8_WAIT_L(n) asm volatile("s_waitcnt lgkmcnt(" #n ")" ::: "memory")
; #define PG8_BAR __builtin_amdgcn_s_barrier()
; #define PG8_SCHED __builtin_amdgcn_sched_barrier(0)
; template <class Epi, class Sched, bool ALIGN_EPI = false, bool SP2 = false>
; __device__ __forceinline__ void gemm_phase(PG8_LAS unsigned char* lds, const Gemm g, const Sched& S, const Epi& E) {
;     ...
;             PG8_LDB(B0, 0, 0); PG8_LDB(B1, 0, 1); PG8_SCHED; PG8_LDA(At, 0, 0); PG8_STAGE(PG8_SA(1, 1), a1 + hstep, voffA);
;             PG8_WAIT_V(8); PG8_WAIT_L(0); PG8_BAR; PG8_MMA(0, 0, At, B0); PG8_MMA(0, 1, At, B1); PG8_BAR; PG8_SCHED;
;     ...
;         if (zero_acc) {
; #pragma unroll
;         for (int a = 0; a < 2; ++a)
; #pragma unroll
;             for (int b = 0; b < 2; ++b)
; #pragma unroll
;                 for (int m = 0; m < 4; ++m)
; #pragma unroll
;                     for (int n = 0; n < 2; ++n) acc[a][b][m][n] = (f32x4){0.f, 0.f, 0.f, 0.f};
;         }
.LBB0_300:
	s_ashr_i32 s13, s12, 31
	s_lshl_b64 s[28:29], s[12:13], 20
	s_add_u32 s28, s43, s28
	s_addc_u32 s29, s44, s29
	s_ashr_i32 s11, s10, 31
	s_lshl_b64 s[30:31], s[10:11], 20
	s_add_u32 s30, s45, s30
	s_addc_u32 s31, s46, s31
	s_and_b64 s[40:41], s[0:1], exec
	s_cselect_b32 s11, s29, s37
	s_cselect_b32 s13, s28, s36
	s_cselect_b32 s56, s31, s39
	s_cselect_b32 s57, s30, s38
	s_add_u32 s36, s36, 0x80080
	s_addc_u32 s37, s37, 0
	s_add_u32 s58, s38, 0x100
	v_mov_b32_e32 v4, 0
	s_addc_u32 s59, s39, 0
	s_mov_b32 s60, -2
	v_mov_b32_e32 v5, v4
	v_mov_b32_e32 v6, v4
	v_mov_b32_e32 v7, v4
	v_mov_b32_e32 v12, v4
	v_mov_b32_e32 v13, v4
	v_mov_b32_e32 v14, v4
	v_mov_b32_e32 v15, v4
	v_mov_b32_e32 v20, v4
	v_mov_b32_e32 v21, v4
	v_mov_b32_e32 v22, v4
	v_mov_b32_e32 v23, v4
	v_mov_b32_e32 v28, v4
	v_mov_b32_e32 v29, v4
	v_mov_b32_e32 v30, v4
	v_mov_b32_e32 v31, v4
	v_mov_b32_e32 v36, v4
	v_mov_b32_e32 v37, v4
	v_mov_b32_e32 v38, v4
	v_mov_b32_e32 v39, v4
	v_mov_b32_e32 v44, v4
	v_mov_b32_e32 v45, v4
	v_mov_b32_e32 v46, v4
	v_mov_b32_e32 v47, v4
	v_mov_b32_e32 v52, v4
	v_mov_b32_e32 v53, v4
	v_mov_b32_e32 v54, v4
	v_mov_b32_e32 v55, v4
	v_mov_b32_e32 v60, v4
	v_mov_b32_e32 v61, v4
	v_mov_b32_e32 v62, v4
	v_mov_b32_e32 v63, v4
	v_mov_b32_e32 v8, v4
	v_mov_b32_e32 v9, v4
	v_mov_b32_e32 v10, v4
	v_mov_b32_e32 v11, v4
	v_mov_b32_e32 v16, v4
	v_mov_b32_e32 v17, v4
	v_mov_b32_e32 v18, v4
	v_mov_b32_e32 v19, v4
	v_mov_b32_e32 v24, v4
	v_mov_b32_e32 v25, v4
	v_mov_b32_e32 v26, v4
	v_mov_b32_e32 v27, v4
	v_mov_b32_e32 v32, v4
	v_mov_b32_e32 v33, v4
	v_mov_b32_e32 v34, v4
	v_mov_b32_e32 v35, v4
	v_mov_b32_e32 v40, v4
	v_mov_b32_e32 v41, v4
	v_mov_b32_e32 v42, v4
	v_mov_b32_e32 v43, v4
	v_mov_b32_e32 v48, v4
	v_mov_b32_e32 v49, v4
	v_mov_b32_e32 v50, v4
	v_mov_b32_e32 v51, v4
	v_mov_b32_e32 v56, v4
	v_mov_b32_e32 v57, v4
	v_mov_b32_e32 v58, v4
	v_mov_b32_e32 v59, v4
	v_mov_b32_e32 v64, v4
	v_mov_b32_e32 v65, v4
	v_mov_b32_e32 v66, v4
	v_mov_b32_e32 v67, v4
	v_mov_b32_e32 v68, v4
	v_mov_b32_e32 v69, v4
	v_mov_b32_e32 v70, v4
	v_mov_b32_e32 v71, v4
	v_mov_b32_e32 v76, v4
	v_mov_b32_e32 v77, v4
	v_mov_b32_e32 v78, v4
	v_mov_b32_e32 v79, v4
	v_mov_b32_e32 v84, v4
	v_mov_b32_e32 v85, v4
	v_mov_b32_e32 v86, v4
	v_mov_b32_e32 v87, v4
	v_mov_b32_e32 v92, v4
	v_mov_b32_e32 v93, v4
	v_mov_b32_e32 v94, v4
	v_mov_b32_e32 v95, v4
	v_mov_b32_e32 v100, v4
	v_mov_b32_e32 v101, v4
	v_mov_b32_e32 v102, v4
	v_mov_b32_e32 v103, v4
	v_mov_b32_e32 v108, v4
	v_mov_b32_e32 v109, v4
	v_mov_b32_e32 v110, v4
	v_mov_b32_e32 v111, v4
	v_mov_b32_e32 v116, v4
	v_mov_b32_e32 v117, v4
	v_mov_b32_e32 v118, v4
	v_mov_b32_e32 v119, v4
	v_mov_b32_e32 v124, v4
	v_mov_b32_e32 v125, v4
	v_mov_b32_e32 v126, v4
	v_mov_b32_e32 v127, v4
	v_mov_b32_e32 v72, v4
	v_mov_b32_e32 v73, v4
	v_mov_b32_e32 v74, v4
	v_mov_b32_e32 v75, v4
	v_mov_b32_e32 v80, v4
	v_mov_b32_e32 v81, v4
	v_mov_b32_e32 v82, v4
	v_mov_b32_e32 v83, v4
	v_mov_b32_e32 v88, v4
	v_mov_b32_e32 v89, v4
	v_mov_b32_e32 v90, v4
	v_mov_b32_e32 v91, v4
	v_mov_b32_e32 v96, v4
	v_mov_b32_e32 v97, v4
	v_mov_b32_e32 v98, v4
	v_mov_b32_e32 v99, v4
	v_mov_b32_e32 v104, v4
	v_mov_b32_e32 v105, v4
	v_mov_b32_e32 v106, v4
	v_mov_b32_e32 v107, v4
	v_mov_b32_e32 v112, v4
	v_mov_b32_e32 v113, v4
	v_mov_b32_e32 v114, v4
	v_mov_b32_e32 v115, v4
	v_mov_b32_e32 v120, v4
	v_mov_b32_e32 v121, v4
	v_mov_b32_e32 v122, v4
	v_mov_b32_e32 v123, v4
	v_mov_b32_e32 v128, v4
	v_mov_b32_e32 v129, v4
	v_mov_b32_e32 v130, v4
	v_mov_b32_e32 v131, v4
	v_add_u32_e32 v249, 0x10000, v150
	.p2align 6
	s_nop 0
.LBB0_301:
	s_add_u32 s38, s36, 0xfff80080
	s_addc_u32 s39, s37, -1
	s_add_i32 s61, 0, 0x10000
	s_cmp_eq_u32 s60, 28
	s_cselect_b32 s41, s11, s39
	s_cselect_b32 s40, s13, s38
	s_cselect_b32 s39, s56, s59
	s_cselect_b32 s38, s57, s58
	s_add_i32 s64, 0, 0x14000
	ds_read_b128 v[142:145], v249
	ds_read_b128 v[146:149], v249 offset:1024
	ds_read_b128 v[154:157], v249 offset:2048
	ds_read_b128 v[158:161], v249 offset:3072
	ds_read_b128 v[174:177], v249 offset:16384
	ds_read_b128 v[178:181], v249 offset:17408
	ds_read_b128 v[204:207], v249 offset:18432
	ds_read_b128 v[208:211], v249 offset:19456
	s_add_i32 m0, s47, 0xc000
	ds_read_b128 v[212:215], v153
	ds_read_b128 v[216:219], v153 offset:1024
	ds_read_b128 v[220:223], v153 offset:2048
	ds_read_b128 v[224:227], v153 offset:3072
	ds_read_b128 v[228:231], v153 offset:4096
	ds_read_b128 v[232:235], v153 offset:5120
	ds_read_b128 v[236:239], v153 offset:6144
	ds_read_b128 v[240:243], v153 offset:7168
	global_load_lds_dwordx4 v138, s[36:37]
	s_add_i32 m0, s47, 0xe000
	s_nop 0
	global_load_lds_dwordx4 v140, s[36:37]
	s_nop 0
	s_waitcnt vmcnt(8) lgkmcnt(0)
	s_barrier
; #define PG8_STAGE(bufoff, gbase, voff) do { _Pragma("unroll") for (int _i = 0; _i < 2; ++_i) \
;         __builtin_amdgcn_global_load_lds((const unsigned*)((const char*)(gbase) + (voff)[_i]), (PG8_LAS unsigned*)(lds + (bufoff) + ldsw + _i * 8192), 16, 0, 0); } while (0)
; #define PG8_LDA(dst, b, h) do { _Pragma("unroll") for (int m = 0; m < 4; ++m) _Pragma("unroll") for (int k = 0; k < 2; ++k) dst[m][k] = *(const PG8_LAS bf16x8*)(lds + PG8_SA(b, h) + aoff + m * 2048 + k * 1024); } while (0)
; #define PG8_MMA(ai, bj, At, Bt) do { __builtin_amdgcn_s_setprio(1); _Pragma("unroll") for (int m = 0; m < 4; ++m) _Pragma("unroll") for (int n = 0; n < 2; ++n) _Pragma("unroll") for (int k = 0; k < 2; ++k) \
;         acc[ai][bj][m][n] = __builtin_amdgcn_mfma_f32_16x16x32_bf16(Bt[n][k], At[m][k], acc[ai][bj][m][n], 0, 0, 0); __builtin_amdgcn_s_setprio(0); } while (0)
; #define PG8_WAIT_V(n) asm volatile("s_waitcnt vmcnt(" #n ")" ::: "memory")
; #define PG8_WAIT_L(n) asm volatile("s_waitcnt lgkmcnt(" #n ")" ::: "memory")
; #define PG8_BAR __builtin_amdgcn_s_barrier()
; #define PG8_SCHED __builtin_amdgcn_sched_barrier(0)
; template <class Epi, class Sched, bool ALIGN_EPI = false, bool SP2 = false>
; __device__ __forceinline__ void gemm_phase(PG8_LAS unsigned char* lds, const Gemm g, const Sched& S, const Epi& E) {
;     ...
;             PG8_WAIT_V(8); PG8_WAIT_L(0); PG8_BAR; PG8_MMA(0, 0, At, B0); PG8_MMA(0, 1, At, B1); PG8_BAR; PG8_SCHED;
;             PG8_LDA(At, 0, 1); PG8_STAGE(PG8_SB(0, 0), b2, voffB); PG8_STAGE(PG8_SB(0, 1), b2 + hstep, voffB); PG8_STAGE(PG8_SA(0, 0), a2, voffA);
;             PG8_WAIT_V(8); PG8_WAIT_L(0); PG8_BAR; PG8_MMA(1, 0, At, B0); PG8_MMA(1, 1, At, B1); PG8_BAR; PG8_SCHED;
	s_setprio 0
	s_waitcnt lgkmcnt(0)
	v_mfma_f32_16x16x32_bf16 v[128:131], v[142:145], v[212:215], v[128:131]
	v_mfma_f32_16x16x32_bf16 v[120:123], v[154:157], v[212:215], v[120:123]
	v_mfma_f32_16x16x32_bf16 v[112:115], v[142:145], v[220:223], v[112:115]
	v_mfma_f32_16x16x32_bf16 v[104:107], v[154:157], v[220:223], v[104:107]
	v_mfma_f32_16x16x32_bf16 v[96:99], v[142:145], v[228:231], v[96:99]
	v_mfma_f32_16x16x32_bf16 v[88:91], v[154:157], v[228:231], v[88:91]
	v_mfma_f32_16x16x32_bf16 v[80:83], v[142:145], v[236:239], v[80:83]
	v_mfma_f32_16x16x32_bf16 v[72:75], v[154:157], v[236:239], v[72:75]
	v_mfma_f32_16x16x32_bf16 v[128:131], v[146:149], v[216:219], v[128:131]
	v_mfma_f32_16x16x32_bf16 v[120:123], v[158:161], v[216:219], v[120:123]
	v_mfma_f32_16x16x32_bf16 v[112:115], v[146:149], v[224:227], v[112:115]
	v_mfma_f32_16x16x32_bf16 v[104:107], v[158:161], v[224:227], v[104:107]
	v_mfma_f32_16x16x32_bf16 v[96:99], v[146:149], v[232:235], v[96:99]
	v_mfma_f32_16x16x32_bf16 v[88:91], v[158:161], v[232:235], v[88:91]
	v_mfma_f32_16x16x32_bf16 v[80:83], v[146:149], v[240:243], v[80:83]
	v_mfma_f32_16x16x32_bf16 v[72:75], v[158:161], v[240:243], v[72:75]
	v_mfma_f32_16x16x32_bf16 v[124:127], v[174:177], v[212:215], v[124:127]
	v_mfma_f32_16x16x32_bf16 v[116:119], v[204:207], v[212:215], v[116:119]
	v_mfma_f32_16x16x32_bf16 v[108:111], v[174:177], v[220:223], v[108:111]
	v_mfma_f32_16x16x32_bf16 v[100:103], v[204:207], v[220:223], v[100:103]
	v_mfma_f32_16x16x32_bf16 v[92:95], v[174:177], v[228:231], v[92:95]
	v_mfma_f32_16x16x32_bf16 v[84:87], v[204:207], v[228:231], v[84:87]
	v_mfma_f32_16x16x32_bf16 v[76:79], v[174:177], v[236:239], v[76:79]
	v_mfma_f32_16x16x32_bf16 v[68:71], v[204:207], v[236:239], v[68:71]
	v_mfma_f32_16x16x32_bf16 v[124:127], v[178:181], v[216:219], v[124:127]
	v_mfma_f32_16x16x32_bf16 v[116:119], v[208:211], v[216:219], v[116:119]
	v_mfma_f32_16x16x32_bf16 v[108:111], v[178:181], v[224:227], v[108:111]
	v_mfma_f32_16x16x32_bf16 v[100:103], v[208:211], v[224:227], v[100:103]
	v_mfma_f32_16x16x32_bf16 v[92:95], v[178:181], v[232:235], v[92:95]
	v_mfma_f32_16x16x32_bf16 v[84:87], v[208:211], v[232:235], v[84:87]
	v_mfma_f32_16x16x32_bf16 v[76:79], v[178:181], v[240:243], v[76:79]
	v_mfma_f32_16x16x32_bf16 v[68:71], v[208:211], v[240:243], v[68:71]
	s_setprio 3
	s_barrier
	s_add_i32 s61, s61, s42
	s_mov_b32 m0, s61
	ds_read_b128 v[212:215], v153 offset:16384
	ds_read_b128 v[216:219], v153 offset:17408
	ds_read_b128 v[220:223], v153 offset:18432
	ds_read_b128 v[224:227], v153 offset:19456
	ds_read_b128 v[228:231], v153 offset:20480
	ds_read_b128 v[232:235], v153 offset:21504
	ds_read_b128 v[236:239], v153 offset:22528
	ds_read_b128 v[240:243], v153 offset:23552
	global_load_lds_dwordx4 v2, s[38:39]
	s_add_i32 m0, s61, 0x2000
	s_add_u32 s62, s38, 0x80000
	s_addc_u32 s63, s39, 0
	s_add_i32 s61, s64, s42
	global_load_lds_dwordx4 v132, s[38:39]
	s_mov_b32 m0, s61
	s_nop 0
	global_load_lds_dwordx4 v2, s[62:63]
	s_add_i32 m0, s61, 0x2000
	s_nop 0
	global_load_lds_dwordx4 v132, s[62:63]
	s_mov_b32 m0, s47
	s_nop 0
	global_load_lds_dwordx4 v136, s[40:41]
	s_mov_b32 m0, s48
	s_nop 0
	global_load_lds_dwordx4 v134, s[40:41]
	s_nop 0
	s_waitcnt vmcnt(8) lgkmcnt(0)
	s_barrier
	s_setprio 0
	s_waitcnt lgkmcnt(0)
	v_mfma_f32_16x16x32_bf16 v[64:67], v[142:145], v[212:215], v[64:67]
	v_mfma_f32_16x16x32_bf16 v[56:59], v[154:157], v[212:215], v[56:59]
	v_mfma_f32_16x16x32_bf16 v[48:51], v[142:145], v[220:223], v[48:51]
	v_mfma_f32_16x16x32_bf16 v[40:43], v[154:157], v[220:223], v[40:43]
	v_mfma_f32_16x16x32_bf16 v[32:35], v[142:145], v[228:231], v[32:35]
	v_mfma_f32_16x16x32_bf16 v[24:27], v[154:157], v[228:231], v[24:27]
	v_mfma_f32_16x16x32_bf16 v[16:19], v[142:145], v[236:239], v[16:19]
	v_mfma_f32_16x16x32_bf16 v[8:11], v[154:157], v[236:239], v[8:11]
	v_mfma_f32_16x16x32_bf16 v[64:67], v[146:149], v[216:219], v[64:67]
	v_mfma_f32_16x16x32_bf16 v[56:59], v[158:161], v[216:219], v[56:59]
	v_mfma_f32_16x16x32_bf16 v[48:51], v[146:149], v[224:227], v[48:51]
	v_mfma_f32_16x16x32_bf16 v[40:43], v[158:161], v[224:227], v[40:43]
	v_mfma_f32_16x16x32_bf16 v[32:35], v[146:149], v[232:235], v[32:35]
	v_mfma_f32_16x16x32_bf16 v[24:27], v[158:161], v[232:235], v[24:27]
	v_mfma_f32_16x16x32_bf16 v[16:19], v[146:149], v[240:243], v[16:19]
	v_mfma_f32_16x16x32_bf16 v[8:11], v[158:161], v[240:243], v[8:11]
	v_mfma_f32_16x16x32_bf16 v[60:63], v[174:177], v[212:215], v[60:63]
	v_mfma_f32_16x16x32_bf16 v[52:55], v[204:207], v[212:215], v[52:55]
	v_mfma_f32_16x16x32_bf16 v[44:47], v[174:177], v[220:223], v[44:47]
	v_mfma_f32_16x16x32_bf16 v[36:39], v[204:207], v[220:223], v[36:39]
	v_mfma_f32_16x16x32_bf16 v[28:31], v[174:177], v[228:231], v[28:31]
	v_mfma_f32_16x16x32_bf16 v[20:23], v[204:207], v[228:231], v[20:23]
	v_mfma_f32_16x16x32_bf16 v[12:15], v[174:177], v[236:239], v[12:15]
	v_mfma_f32_16x16x32_bf16 v[4:7], v[204:207], v[236:239], v[4:7]
	v_mfma_f32_16x16x32_bf16 v[60:63], v[178:181], v[216:219], v[60:63]
	v_mfma_f32_16x16x32_bf16 v[52:55], v[208:211], v[216:219], v[52:55]
	v_mfma_f32_16x16x32_bf16 v[44:47], v[178:181], v[224:227], v[44:47]
	v_mfma_f32_16x16x32_bf16 v[36:39], v[208:211], v[224:227], v[36:39]
	v_mfma_f32_16x16x32_bf16 v[28:31], v[178:181], v[232:235], v[28:31]
	v_mfma_f32_16x16x32_bf16 v[20:23], v[208:211], v[232:235], v[20:23]
	v_mfma_f32_16x16x32_bf16 v[12:15], v[178:181], v[240:243], v[12:15]
	v_mfma_f32_16x16x32_bf16 v[4:7], v[208:211], v[240:243], v[4:7]
	s_setprio 3
	s_barrier
; #define PG8_STAGE(bufoff, gbase, voff) do { _Pragma("unroll") for (int _i = 0; _i < 2; ++_i) \
;         __builtin_amdgcn_global_load_lds((const unsigned*)((const char*)(gbase) + (voff)[_i]), (PG8_LAS unsigned*)(lds + (bufoff) + ldsw + _i * 8192), 16, 0, 0); } while (0)
; #define PG8_LDA(dst, b, h) do { _Pragma("unroll") for (int m = 0; m < 4; ++m) _Pragma("unroll") for (int k = 0; k < 2; ++k) dst[m][k] = *(const PG8_LAS bf16x8*)(lds + PG8_SA(b, h) + aoff + m * 2048 + k * 1024); } while (0)
; #define PG8_LDB(dst, b, h) do { _Pragma("unroll") for (int n = 0; n < 2; ++n) _Pragma("unroll") for (int k = 0; k < 2; ++k) dst[n][k] = *(const PG8_LAS bf16x8*)(lds + PG8_SB(b, h) + boff + n * 2048 + k * 1024); } while (0)
; #define PG8_MMA(ai, bj, At, Bt) do { __builtin_amdgcn_s_setprio(1); _Pragma("unroll") for (int m = 0; m < 4; ++m) _Pragma("unroll") for (int n = 0; n < 2; ++n) _Pragma("unroll") for (int k = 0; k < 2; ++k) \
;         acc[ai][bj][m][n] = __builtin_amdgcn_mfma_f32_16x16x32_bf16(Bt[n][k], At[m][k], acc[ai][bj][m][n], 0, 0, 0); __builtin_amdgcn_s_setprio(0); } while (0)
; #define PG8_WAIT_V(n) asm volatile("s_waitcnt vmcnt(" #n ")" ::: "memory")
; #define PG8_WAIT_L(n) asm volatile("s_waitcnt lgkmcnt(" #n ")" ::: "memory")
; #define PG8_BAR __builtin_amdgcn_s_barrier()
; #define PG8_SCHED __builtin_amdgcn_sched_barrier(0)
; template <class Epi, class Sched, bool ALIGN_EPI = false, bool SP2 = false>
; __device__ __forceinline__ void gemm_phase(PG8_LAS unsigned char* lds, const Gemm g, const Sched& S, const Epi& E) {
;     ...
;             PG8_LDB(B0, 1, 0); PG8_LDB(B1, 1, 1); PG8_SCHED; PG8_LDA(At, 1, 0); PG8_STAGE(PG8_SA(0, 1), a2 + hstep, voffA);
;             PG8_WAIT_V(8); PG8_WAIT_L(0); PG8_BAR; PG8_MMA(0, 0, At, B0); PG8_MMA(0, 1, At, B1); PG8_BAR; PG8_SCHED;
;             PG8_LDA(At, 1, 1); PG8_STAGE(PG8_SB(1, 0), b3, voffB); PG8_STAGE(PG8_SB(1, 1), b3 + hstep, voffB); PG8_STAGE(PG8_SA(1, 0), a3, voffA);
;             PG8_WAIT_V(8); PG8_WAIT_L(0); PG8_BAR; PG8_MMA(1, 0, At, B0); PG8_MMA(1, 1, At, B1); PG8_BAR; PG8_SCHED;
	s_add_i32 s61, 0, 0x18000
	s_add_i32 s62, 0, 0x1c000
	ds_read_b128 v[142:145], v249 offset:32768
	ds_read_b128 v[146:149], v249 offset:33792
	ds_read_b128 v[154:157], v249 offset:34816
	ds_read_b128 v[158:161], v249 offset:35840
	ds_read_b128 v[174:177], v249 offset:49152
	ds_read_b128 v[178:181], v249 offset:50176
	ds_read_b128 v[204:207], v249 offset:51200
	ds_read_b128 v[208:211], v249 offset:52224
	s_add_u32 s100, s40, 0x80
	s_addc_u32 s101, s41, 0
	s_add_u32 s40, s40, 0x80000
	s_addc_u32 s41, s41, 0
	s_mov_b32 m0, s49
	ds_read_b128 v[212:215], v153 offset:32768
	ds_read_b128 v[216:219], v153 offset:33792
	ds_read_b128 v[220:223], v153 offset:34816
	ds_read_b128 v[224:227], v153 offset:35840
	ds_read_b128 v[228:231], v153 offset:36864
	ds_read_b128 v[232:235], v153 offset:37888
	ds_read_b128 v[236:239], v153 offset:38912
	ds_read_b128 v[240:243], v153 offset:39936
	global_load_lds_dwordx4 v136, s[40:41]
	s_mov_b32 m0, s50
	s_nop 0
	global_load_lds_dwordx4 v134, s[40:41]
	s_nop 0
	s_waitcnt vmcnt(8) lgkmcnt(0)
	s_barrier
	s_setprio 0
	s_waitcnt lgkmcnt(0)
	v_mfma_f32_16x16x32_bf16 v[128:131], v[142:145], v[212:215], v[128:131]
	v_mfma_f32_16x16x32_bf16 v[120:123], v[154:157], v[212:215], v[120:123]
	v_mfma_f32_16x16x32_bf16 v[112:115], v[142:145], v[220:223], v[112:115]
	v_mfma_f32_16x16x32_bf16 v[104:107], v[154:157], v[220:223], v[104:107]
	v_mfma_f32_16x16x32_bf16 v[96:99], v[142:145], v[228:231], v[96:99]
	v_mfma_f32_16x16x32_bf16 v[88:91], v[154:157], v[228:231], v[88:91]
	v_mfma_f32_16x16x32_bf16 v[80:83], v[142:145], v[236:239], v[80:83]
	v_mfma_f32_16x16x32_bf16 v[72:75], v[154:157], v[236:239], v[72:75]
	v_mfma_f32_16x16x32_bf16 v[128:131], v[146:149], v[216:219], v[128:131]
	v_mfma_f32_16x16x32_bf16 v[120:123], v[158:161], v[216:219], v[120:123]
	v_mfma_f32_16x16x32_bf16 v[112:115], v[146:149], v[224:227], v[112:115]
	v_mfma_f32_16x16x32_bf16 v[104:107], v[158:161], v[224:227], v[104:107]
	v_mfma_f32_16x16x32_bf16 v[96:99], v[146:149], v[232:235], v[96:99]
	v_mfma_f32_16x16x32_bf16 v[88:91], v[158:161], v[232:235], v[88:91]
	v_mfma_f32_16x16x32_bf16 v[80:83], v[146:149], v[240:243], v[80:83]
	v_mfma_f32_16x16x32_bf16 v[72:75], v[158:161], v[240:243], v[72:75]
	v_mfma_f32_16x16x32_bf16 v[124:127], v[174:177], v[212:215], v[124:127]
	v_mfma_f32_16x16x32_bf16 v[116:119], v[204:207], v[212:215], v[116:119]
	v_mfma_f32_16x16x32_bf16 v[108:111], v[174:177], v[220:223], v[108:111]
	v_mfma_f32_16x16x32_bf16 v[100:103], v[204:207], v[220:223], v[100:103]
	v_mfma_f32_16x16x32_bf16 v[92:95], v[174:177], v[228:231], v[92:95]
	v_mfma_f32_16x16x32_bf16 v[84:87], v[204:207], v[228:231], v[84:87]
	v_mfma_f32_16x16x32_bf16 v[76:79], v[174:177], v[236:239], v[76:79]
	v_mfma_f32_16x16x32_bf16 v[68:71], v[204:207], v[236:239], v[68:71]
	v_mfma_f32_16x16x32_bf16 v[124:127], v[178:181], v[216:219], v[124:127]
	v_mfma_f32_16x16x32_bf16 v[116:119], v[208:211], v[216:219], v[116:119]
	v_mfma_f32_16x16x32_bf16 v[108:111], v[178:181], v[224:227], v[108:111]
	v_mfma_f32_16x16x32_bf16 v[100:103], v[208:211], v[224:227], v[100:103]
	v_mfma_f32_16x16x32_bf16 v[92:95], v[178:181], v[232:235], v[92:95]
	v_mfma_f32_16x16x32_bf16 v[84:87], v[208:211], v[232:235], v[84:87]
	v_mfma_f32_16x16x32_bf16 v[76:79], v[178:181], v[240:243], v[76:79]
	v_mfma_f32_16x16x32_bf16 v[68:71], v[208:211], v[240:243], v[68:71]
	s_setprio 3
	s_barrier
	s_add_i32 s40, s61, s42
	s_add_i32 m0, s40, 0xffffff80
	ds_read_b128 v[212:215], v153 offset:49152
	ds_read_b128 v[216:219], v153 offset:50176
	ds_read_b128 v[220:223], v153 offset:51200
	ds_read_b128 v[224:227], v153 offset:52224
	ds_read_b128 v[228:231], v153 offset:53248
	ds_read_b128 v[232:235], v153 offset:54272
	ds_read_b128 v[236:239], v153 offset:55296
	ds_read_b128 v[240:243], v153 offset:56320
	global_load_lds_dwordx4 v2, s[38:39] offset:128
	s_add_i32 m0, s40, 0x1f80
	s_add_i32 s40, s62, s42
	global_load_lds_dwordx4 v132, s[38:39] offset:128
	s_add_u32 s38, s38, 0x80080
	s_addc_u32 s39, s39, 0
	s_mov_b32 m0, s40
	s_nop 0
	global_load_lds_dwordx4 v2, s[38:39]
	s_add_i32 m0, s40, 0x2000
	s_nop 0
	global_load_lds_dwordx4 v132, s[38:39]
	s_mov_b32 m0, s51
	s_nop 0
	global_load_lds_dwordx4 v136, s[100:101]
	s_mov_b32 m0, s53
	s_nop 0
	global_load_lds_dwordx4 v134, s[100:101]
	s_waitcnt vmcnt(8) lgkmcnt(0)
	s_barrier
	s_setprio 0
	s_waitcnt lgkmcnt(0)
	v_mfma_f32_16x16x32_bf16 v[64:67], v[142:145], v[212:215], v[64:67]
	v_mfma_f32_16x16x32_bf16 v[56:59], v[154:157], v[212:215], v[56:59]
	v_mfma_f32_16x16x32_bf16 v[48:51], v[142:145], v[220:223], v[48:51]
	v_mfma_f32_16x16x32_bf16 v[40:43], v[154:157], v[220:223], v[40:43]
	v_mfma_f32_16x16x32_bf16 v[32:35], v[142:145], v[228:231], v[32:35]
	v_mfma_f32_16x16x32_bf16 v[24:27], v[154:157], v[228:231], v[24:27]
	v_mfma_f32_16x16x32_bf16 v[16:19], v[142:145], v[236:239], v[16:19]
	v_mfma_f32_16x16x32_bf16 v[8:11], v[154:157], v[236:239], v[8:11]
	v_mfma_f32_16x16x32_bf16 v[64:67], v[146:149], v[216:219], v[64:67]
	v_mfma_f32_16x16x32_bf16 v[56:59], v[158:161], v[216:219], v[56:59]
	v_mfma_f32_16x16x32_bf16 v[48:51], v[146:149], v[224:227], v[48:51]
	v_mfma_f32_16x16x32_bf16 v[40:43], v[158:161], v[224:227], v[40:43]
	v_mfma_f32_16x16x32_bf16 v[32:35], v[146:149], v[232:235], v[32:35]
	v_mfma_f32_16x16x32_bf16 v[24:27], v[158:161], v[232:235], v[24:27]
	v_mfma_f32_16x16x32_bf16 v[16:19], v[146:149], v[240:243], v[16:19]
	v_mfma_f32_16x16x32_bf16 v[8:11], v[158:161], v[240:243], v[8:11]
	v_mfma_f32_16x16x32_bf16 v[60:63], v[174:177], v[212:215], v[60:63]
	v_mfma_f32_16x16x32_bf16 v[52:55], v[204:207], v[212:215], v[52:55]
	v_mfma_f32_16x16x32_bf16 v[44:47], v[174:177], v[220:223], v[44:47]
	v_mfma_f32_16x16x32_bf16 v[36:39], v[204:207], v[220:223], v[36:39]
	v_mfma_f32_16x16x32_bf16 v[28:31], v[174:177], v[228:231], v[28:31]
	v_mfma_f32_16x16x32_bf16 v[20:23], v[204:207], v[228:231], v[20:23]
	v_mfma_f32_16x16x32_bf16 v[12:15], v[174:177], v[236:239], v[12:15]
	v_mfma_f32_16x16x32_bf16 v[4:7], v[204:207], v[236:239], v[4:7]
	v_mfma_f32_16x16x32_bf16 v[60:63], v[178:181], v[216:219], v[60:63]
	v_mfma_f32_16x16x32_bf16 v[52:55], v[208:211], v[216:219], v[52:55]
	v_mfma_f32_16x16x32_bf16 v[44:47], v[178:181], v[224:227], v[44:47]
	v_mfma_f32_16x16x32_bf16 v[36:39], v[208:211], v[224:227], v[36:39]
	v_mfma_f32_16x16x32_bf16 v[28:31], v[178:181], v[232:235], v[28:31]
	v_mfma_f32_16x16x32_bf16 v[20:23], v[208:211], v[232:235], v[20:23]
	v_mfma_f32_16x16x32_bf16 v[12:15], v[178:181], v[240:243], v[12:15]
	v_mfma_f32_16x16x32_bf16 v[4:7], v[208:211], v[240:243], v[4:7]
	s_setprio 3
	s_barrier
	s_add_i32 s60, s60, 2
	s_add_u32 s36, s36, 0x100
	s_addc_u32 s37, s37, 0
	s_add_u32 s58, s58, 0x100
	s_addc_u32 s59, s59, 0
	s_cmp_gt_u32 s60, 29
	s_cbranch_scc0 .LBB0_301
	s_and_b64 vcc, exec, s[8:9]
	s_cbranch_vccz .LBB0_304
	s_barrier

; #define PG8_STAGE(bufoff, gbase, voff) do { _Pragma("unroll") for (int _i = 0; _i < 2; ++_i) \
;         __builtin_amdgcn_global_load_lds((const unsigned*)((const char*)(gbase) + (voff)[_i]), (PG8_LAS unsigned*)(lds + (bufoff) + ldsw + _i * 8192), 16, 0, 0); } while (0)
; #define PG8_LDA(dst, b, h) do { _Pragma("unroll") for (int m = 0; m < 4; ++m) _Pragma("unroll") for (int k = 0; k < 2; ++k) dst[m][k] = *(const PG8_LAS bf16x8*)(lds + PG8_SA(b, h) + aoff + m * 2048 + k * 1024); } while (0)
; #define PG8_LDB(dst, b, h) do { _Pragma("unroll") for (int n = 0; n < 2; ++n) _Pragma("unroll") for (int k = 0; k < 2; ++k) dst[n][k] = *(const PG8_LAS bf16x8*)(lds + PG8_SB(b, h) + boff + n * 2048 + k * 1024); } while (0)
; #define PG8_MMA(ai, bj, At, Bt) do { __builtin_amdgcn_s_setprio(1); _Pragma("unroll") for (int m = 0; m < 4; ++m) _Pragma("unroll") for (int n = 0; n < 2; ++n) _Pragma("unroll") for (int k = 0; k < 2; ++k) \
;         acc[ai][bj][m][n] = __builtin_amdgcn_mfma_f32_16x16x32_bf16(Bt[n][k], At[m][k], acc[ai][bj][m][n], 0, 0, 0); __builtin_amdgcn_s_setprio(0); } while (0)
; #define PG8_WAIT_V(n) asm volatile("s_waitcnt vmcnt(" #n ")" ::: "memory")
; #define PG8_WAIT_L(n) asm volatile("s_waitcnt lgkmcnt(" #n ")" ::: "memory")
; #define PG8_BAR __builtin_amdgcn_s_barrier()
; #define PG8_SCHED __builtin_amdgcn_sched_barrier(0)
; template <class Epi, class Sched, bool ALIGN_EPI = false, bool SP2 = false>
; __device__ __forceinline__ void gemm_phase(PG8_LAS unsigned char* lds, const Gemm g, const Sched& S, const Epi& E) {
;     ...
;             PG8_LDB(B0, 0, 0); PG8_LDB(B1, 0, 1); PG8_SCHED; PG8_LDA(At, 0, 0); PG8_STAGE(PG8_SA(1, 1), a1 + hstep, voffA);
;             PG8_WAIT_V(8); PG8_WAIT_L(0); PG8_BAR; PG8_MMA(0, 0, At, B0); PG8_MMA(0, 1, At, B1); PG8_BAR; PG8_SCHED;
;     ...
;         if (zero_acc) {
; #pragma unroll
;         for (int a = 0; a < 2; ++a)
; #pragma unroll
;             for (int b = 0; b < 2; ++b)
; #pragma unroll
;                 for (int m = 0; m < 4; ++m)
; #pragma unroll
;                     for (int n = 0; n < 2; ++n) acc[a][b][m][n] = (f32x4){0.f, 0.f, 0.f, 0.f};
;         }
.LBB0_574:
	s_add_u32 s61, s36, 0x100
	v_mov_b32_e32 v4, 0
	s_addc_u32 s62, s37, 0
	s_mov_b32 s63, -2
	s_waitcnt lgkmcnt(0)
	v_mov_b32_e32 v5, v4
	v_mov_b32_e32 v6, v4
	v_mov_b32_e32 v7, v4
	v_mov_b32_e32 v8, v4
	v_mov_b32_e32 v9, v4
	v_mov_b32_e32 v10, v4
	v_mov_b32_e32 v11, v4
	v_mov_b32_e32 v20, v4
	v_mov_b32_e32 v21, v4
	s_waitcnt vmcnt(0)
	v_mov_b32_e32 v22, v4
	v_mov_b32_e32 v23, v4
	v_mov_b32_e32 v24, v4
	v_mov_b32_e32 v25, v4
	v_mov_b32_e32 v26, v4
	v_mov_b32_e32 v27, v4
	v_mov_b32_e32 v36, v4
	v_mov_b32_e32 v37, v4
	v_mov_b32_e32 v38, v4
	v_mov_b32_e32 v39, v4
	v_mov_b32_e32 v40, v4
	v_mov_b32_e32 v41, v4
	v_mov_b32_e32 v42, v4
	v_mov_b32_e32 v43, v4
	v_mov_b32_e32 v52, v4
	v_mov_b32_e32 v53, v4
	v_mov_b32_e32 v54, v4
	v_mov_b32_e32 v55, v4
	v_mov_b32_e32 v56, v4
	v_mov_b32_e32 v57, v4
	v_mov_b32_e32 v58, v4
	v_mov_b32_e32 v59, v4
	v_mov_b32_e32 v12, v4
	v_mov_b32_e32 v13, v4
	v_mov_b32_e32 v14, v4
	v_mov_b32_e32 v15, v4
	v_mov_b32_e32 v16, v4
	v_mov_b32_e32 v17, v4
	v_mov_b32_e32 v18, v4
	v_mov_b32_e32 v19, v4
	v_mov_b32_e32 v28, v4
	v_mov_b32_e32 v29, v4
	v_mov_b32_e32 v30, v4
	v_mov_b32_e32 v31, v4
	v_mov_b32_e32 v32, v4
	v_mov_b32_e32 v33, v4
	v_mov_b32_e32 v34, v4
	v_mov_b32_e32 v35, v4
	v_mov_b32_e32 v44, v4
	v_mov_b32_e32 v45, v4
	v_mov_b32_e32 v46, v4
	v_mov_b32_e32 v47, v4
	v_mov_b32_e32 v48, v4
	v_mov_b32_e32 v49, v4
	v_mov_b32_e32 v50, v4
	v_mov_b32_e32 v51, v4
	v_mov_b32_e32 v60, v4
	v_mov_b32_e32 v61, v4
	v_mov_b32_e32 v62, v4
	v_mov_b32_e32 v63, v4
	v_mov_b32_e32 v64, v4
	v_mov_b32_e32 v65, v4
	v_mov_b32_e32 v66, v4
	v_mov_b32_e32 v67, v4
	v_mov_b32_e32 v68, v4
	v_mov_b32_e32 v69, v4
	v_mov_b32_e32 v70, v4
	v_mov_b32_e32 v71, v4
	v_mov_b32_e32 v72, v4
	v_mov_b32_e32 v73, v4
	v_mov_b32_e32 v74, v4
	v_mov_b32_e32 v75, v4
	v_mov_b32_e32 v84, v4
	v_mov_b32_e32 v85, v4
	v_mov_b32_e32 v86, v4
	v_mov_b32_e32 v87, v4
	v_mov_b32_e32 v88, v4
	v_mov_b32_e32 v89, v4
	v_mov_b32_e32 v90, v4
	v_mov_b32_e32 v91, v4
	v_mov_b32_e32 v100, v4
	v_mov_b32_e32 v101, v4
	v_mov_b32_e32 v102, v4
	v_mov_b32_e32 v103, v4
	v_mov_b32_e32 v104, v4
	v_mov_b32_e32 v105, v4
	v_mov_b32_e32 v106, v4
	v_mov_b32_e32 v107, v4
	v_mov_b32_e32 v116, v4
	v_mov_b32_e32 v117, v4
	v_mov_b32_e32 v118, v4
	v_mov_b32_e32 v119, v4
	v_mov_b32_e32 v120, v4
	v_mov_b32_e32 v121, v4
	v_mov_b32_e32 v122, v4
	v_mov_b32_e32 v123, v4
	v_mov_b32_e32 v76, v4
	v_mov_b32_e32 v77, v4
	v_mov_b32_e32 v78, v4
	v_mov_b32_e32 v79, v4
	v_mov_b32_e32 v80, v4
	v_mov_b32_e32 v81, v4
	v_mov_b32_e32 v82, v4
	v_mov_b32_e32 v83, v4
	v_mov_b32_e32 v92, v4
	v_mov_b32_e32 v93, v4
	v_mov_b32_e32 v94, v4
	v_mov_b32_e32 v95, v4
	v_mov_b32_e32 v96, v4
	v_mov_b32_e32 v97, v4
	v_mov_b32_e32 v98, v4
	v_mov_b32_e32 v99, v4
	v_mov_b32_e32 v108, v4
	v_mov_b32_e32 v109, v4
	v_mov_b32_e32 v110, v4
	v_mov_b32_e32 v111, v4
	v_mov_b32_e32 v112, v4
	v_mov_b32_e32 v113, v4
	v_mov_b32_e32 v114, v4
	v_mov_b32_e32 v115, v4
	v_mov_b32_e32 v124, v4
	v_mov_b32_e32 v125, v4
	v_mov_b32_e32 v126, v4
	v_mov_b32_e32 v127, v4
	v_mov_b32_e32 v128, v4
	v_mov_b32_e32 v129, v4
	v_mov_b32_e32 v130, v4
	v_mov_b32_e32 v131, v4
	v_add_u32_e32 v247, 0x10000, v173
	.p2align 6
	s_nop 0
.LBB0_575:
	s_add_u32 s36, s34, 0x100
	s_addc_u32 s37, s35, 0
	s_add_i32 s64, 0, 0x10000
	s_cmpk_eq_i32 s63, 0x52
	s_cselect_b32 s41, s5, s37
	s_cselect_b32 s40, s4, s36
	s_cselect_b32 s39, s31, s62
	s_cselect_b32 s38, s30, s61
	s_add_i32 s65, 0, 0x14000
	ds_read_b128 v[142:145], v247
	ds_read_b128 v[146:149], v247 offset:1024
	ds_read_b128 v[150:153], v247 offset:2048
	ds_read_b128 v[154:157], v247 offset:3072
	ds_read_b128 v[158:161], v247 offset:16384
	ds_read_b128 v[174:177], v247 offset:17408
	ds_read_b128 v[180:183], v247 offset:18432
	ds_read_b128 v[204:207], v247 offset:19456
	v_lshl_add_u64 v[162:163], s[34:35], 0, v[138:139]
	s_add_i32 m0, s47, 0xc000
	ds_read_b128 v[208:211], v179
	ds_read_b128 v[212:215], v179 offset:1024
	ds_read_b128 v[216:219], v179 offset:2048
	ds_read_b128 v[220:223], v179 offset:3072
	ds_read_b128 v[224:227], v179 offset:4096
	ds_read_b128 v[228:231], v179 offset:5120
	ds_read_b128 v[232:235], v179 offset:6144
	ds_read_b128 v[236:239], v179 offset:7168
	global_load_lds_dwordx4 v[162:163], off
	v_lshl_add_u64 v[162:163], s[34:35], 0, v[140:141]
	s_add_i32 m0, s47, 0xe000
	s_nop 0
	global_load_lds_dwordx4 v[162:163], off
	s_nop 0
	s_waitcnt vmcnt(8) lgkmcnt(0)
	s_barrier
	s_setprio 0
	s_waitcnt lgkmcnt(0)
	v_mfma_f32_16x16x32_bf16 v[128:131], v[142:145], v[208:211], v[128:131]
	v_mfma_f32_16x16x32_bf16 v[124:127], v[150:153], v[208:211], v[124:127]
	v_mfma_f32_16x16x32_bf16 v[112:115], v[142:145], v[216:219], v[112:115]
	v_mfma_f32_16x16x32_bf16 v[108:111], v[150:153], v[216:219], v[108:111]
	v_mfma_f32_16x16x32_bf16 v[96:99], v[142:145], v[224:227], v[96:99]
	v_mfma_f32_16x16x32_bf16 v[92:95], v[150:153], v[224:227], v[92:95]
	v_mfma_f32_16x16x32_bf16 v[80:83], v[142:145], v[232:235], v[80:83]
	v_mfma_f32_16x16x32_bf16 v[76:79], v[150:153], v[232:235], v[76:79]
	v_mfma_f32_16x16x32_bf16 v[128:131], v[146:149], v[212:215], v[128:131]
	v_mfma_f32_16x16x32_bf16 v[124:127], v[154:157], v[212:215], v[124:127]
	v_mfma_f32_16x16x32_bf16 v[112:115], v[146:149], v[220:223], v[112:115]
	v_mfma_f32_16x16x32_bf16 v[108:111], v[154:157], v[220:223], v[108:111]
	v_mfma_f32_16x16x32_bf16 v[96:99], v[146:149], v[228:231], v[96:99]
	v_mfma_f32_16x16x32_bf16 v[92:95], v[154:157], v[228:231], v[92:95]
	v_mfma_f32_16x16x32_bf16 v[80:83], v[146:149], v[236:239], v[80:83]
	v_mfma_f32_16x16x32_bf16 v[76:79], v[154:157], v[236:239], v[76:79]
	v_mfma_f32_16x16x32_bf16 v[120:123], v[158:161], v[208:211], v[120:123]
	v_mfma_f32_16x16x32_bf16 v[116:119], v[180:183], v[208:211], v[116:119]
	v_mfma_f32_16x16x32_bf16 v[104:107], v[158:161], v[216:219], v[104:107]
	v_mfma_f32_16x16x32_bf16 v[100:103], v[180:183], v[216:219], v[100:103]
	v_mfma_f32_16x16x32_bf16 v[88:91], v[158:161], v[224:227], v[88:91]
	v_mfma_f32_16x16x32_bf16 v[84:87], v[180:183], v[224:227], v[84:87]
	v_mfma_f32_16x16x32_bf16 v[72:75], v[158:161], v[232:235], v[72:75]
	v_mfma_f32_16x16x32_bf16 v[68:71], v[180:183], v[232:235], v[68:71]
	v_mfma_f32_16x16x32_bf16 v[120:123], v[174:177], v[212:215], v[120:123]
	v_mfma_f32_16x16x32_bf16 v[116:119], v[204:207], v[212:215], v[116:119]
	v_mfma_f32_16x16x32_bf16 v[104:107], v[174:177], v[220:223], v[104:107]
	v_mfma_f32_16x16x32_bf16 v[100:103], v[204:207], v[220:223], v[100:103]
	v_mfma_f32_16x16x32_bf16 v[88:91], v[174:177], v[228:231], v[88:91]
	v_mfma_f32_16x16x32_bf16 v[84:87], v[204:207], v[228:231], v[84:87]
	v_mfma_f32_16x16x32_bf16 v[72:75], v[174:177], v[236:239], v[72:75]
	v_mfma_f32_16x16x32_bf16 v[68:71], v[204:207], v[236:239], v[68:71]
	s_setprio 3
	s_barrier
; #define PG8_STAGE(bufoff, gbase, voff) do { _Pragma("unroll") for (int _i = 0; _i < 2; ++_i) \
;         __builtin_amdgcn_global_load_lds((const unsigned*)((const char*)(gbase) + (voff)[_i]), (PG8_LAS unsigned*)(lds + (bufoff) + ldsw + _i * 8192), 16, 0, 0); } while (0)
; #define PG8_LDA(dst, b, h) do { _Pragma("unroll") for (int m = 0; m < 4; ++m) _Pragma("unroll") for (int k = 0; k < 2; ++k) dst[m][k] = *(const PG8_LAS bf16x8*)(lds + PG8_SA(b, h) + aoff + m * 2048 + k * 1024); } while (0)
; #define PG8_LDB(dst, b, h) do { _Pragma("unroll") for (int n = 0; n < 2; ++n) _Pragma("unroll") for (int k = 0; k < 2; ++k) dst[n][k] = *(const PG8_LAS bf16x8*)(lds + PG8_SB(b, h) + boff + n * 2048 + k * 1024); } while (0)
; #define PG8_MMA(ai, bj, At, Bt) do { __builtin_amdgcn_s_setprio(1); _Pragma("unroll") for (int m = 0; m < 4; ++m) _Pragma("unroll") for (int n = 0; n < 2; ++n) _Pragma("unroll") for (int k = 0; k < 2; ++k) \
;         acc[ai][bj][m][n] = __builtin_amdgcn_mfma_f32_16x16x32_bf16(Bt[n][k], At[m][k], acc[ai][bj][m][n], 0, 0, 0); __builtin_amdgcn_s_setprio(0); } while (0)
; #define PG8_WAIT_V(n) asm volatile("s_waitcnt vmcnt(" #n ")" ::: "memory")
; #define PG8_WAIT_L(n) asm volatile("s_waitcnt lgkmcnt(" #n ")" ::: "memory")
; #define PG8_BAR __builtin_amdgcn_s_barrier()
; #define PG8_SCHED __builtin_amdgcn_sched_barrier(0)
; template <class Epi, class Sched, bool ALIGN_EPI = false, bool SP2 = false>
; __device__ __forceinline__ void gemm_phase(PG8_LAS unsigned char* lds, const Gemm g, const Sched& S, const Epi& E) {
;     ...
;             PG8_LDA(At, 0, 1); PG8_STAGE(PG8_SB(0, 0), b2, voffB); PG8_STAGE(PG8_SB(0, 1), b2 + hstep, voffB); PG8_STAGE(PG8_SA(0, 0), a2, voffA);
;             PG8_WAIT_V(8); PG8_WAIT_L(0); PG8_BAR; PG8_MMA(1, 0, At, B0); PG8_MMA(1, 1, At, B1); PG8_BAR; PG8_SCHED;
;             PG8_LDB(B0, 1, 0); PG8_LDB(B1, 1, 1); PG8_SCHED; PG8_LDA(At, 1, 0); PG8_STAGE(PG8_SA(0, 1), a2 + hstep, voffA);
	s_add_i32 s34, s64, s46
	s_mov_b32 m0, s34
	ds_read_b128 v[208:211], v179 offset:16384
	ds_read_b128 v[212:215], v179 offset:17408
	ds_read_b128 v[216:219], v179 offset:18432
	ds_read_b128 v[220:223], v179 offset:19456
	ds_read_b128 v[224:227], v179 offset:20480
	ds_read_b128 v[228:231], v179 offset:21504
	ds_read_b128 v[232:235], v179 offset:22528
	ds_read_b128 v[236:239], v179 offset:23552
	global_load_lds_dwordx4 v2, s[38:39]
	s_add_i32 m0, s34, 0x2000
	s_add_u32 s34, s38, 0x158000
	s_addc_u32 s35, s39, 0
	s_add_i32 s64, s65, s46
	global_load_lds_dwordx4 v132, s[38:39]
	s_mov_b32 m0, s64
	s_nop 0
	global_load_lds_dwordx4 v2, s[34:35]
	s_add_i32 m0, s64, 0x2000
	s_nop 0
	global_load_lds_dwordx4 v132, s[34:35]
	s_mov_b32 m0, s47
	s_nop 0
	global_load_lds_dwordx4 v2, s[40:41]
	s_mov_b32 m0, s48
	s_nop 0
	global_load_lds_dwordx4 v132, s[40:41]
	s_nop 0
	s_waitcnt vmcnt(8) lgkmcnt(0)
	s_barrier
	s_setprio 0
	s_waitcnt lgkmcnt(0)
	v_mfma_f32_16x16x32_bf16 v[64:67], v[142:145], v[208:211], v[64:67]
	v_mfma_f32_16x16x32_bf16 v[60:63], v[150:153], v[208:211], v[60:63]
	v_mfma_f32_16x16x32_bf16 v[48:51], v[142:145], v[216:219], v[48:51]
	v_mfma_f32_16x16x32_bf16 v[44:47], v[150:153], v[216:219], v[44:47]
	v_mfma_f32_16x16x32_bf16 v[32:35], v[142:145], v[224:227], v[32:35]
	v_mfma_f32_16x16x32_bf16 v[28:31], v[150:153], v[224:227], v[28:31]
	v_mfma_f32_16x16x32_bf16 v[16:19], v[142:145], v[232:235], v[16:19]
	v_mfma_f32_16x16x32_bf16 v[12:15], v[150:153], v[232:235], v[12:15]
	v_mfma_f32_16x16x32_bf16 v[64:67], v[146:149], v[212:215], v[64:67]
	v_mfma_f32_16x16x32_bf16 v[60:63], v[154:157], v[212:215], v[60:63]
	v_mfma_f32_16x16x32_bf16 v[48:51], v[146:149], v[220:223], v[48:51]
	v_mfma_f32_16x16x32_bf16 v[44:47], v[154:157], v[220:223], v[44:47]
	v_mfma_f32_16x16x32_bf16 v[32:35], v[146:149], v[228:231], v[32:35]
	v_mfma_f32_16x16x32_bf16 v[28:31], v[154:157], v[228:231], v[28:31]
	v_mfma_f32_16x16x32_bf16 v[16:19], v[146:149], v[236:239], v[16:19]
	v_mfma_f32_16x16x32_bf16 v[12:15], v[154:157], v[236:239], v[12:15]
	v_mfma_f32_16x16x32_bf16 v[56:59], v[158:161], v[208:211], v[56:59]
	v_mfma_f32_16x16x32_bf16 v[52:55], v[180:183], v[208:211], v[52:55]
	v_mfma_f32_16x16x32_bf16 v[40:43], v[158:161], v[216:219], v[40:43]
	v_mfma_f32_16x16x32_bf16 v[36:39], v[180:183], v[216:219], v[36:39]
	v_mfma_f32_16x16x32_bf16 v[24:27], v[158:161], v[224:227], v[24:27]
	v_mfma_f32_16x16x32_bf16 v[20:23], v[180:183], v[224:227], v[20:23]
	v_mfma_f32_16x16x32_bf16 v[8:11], v[158:161], v[232:235], v[8:11]
	v_mfma_f32_16x16x32_bf16 v[4:7], v[180:183], v[232:235], v[4:7]
	v_mfma_f32_16x16x32_bf16 v[56:59], v[174:177], v[212:215], v[56:59]
	v_mfma_f32_16x16x32_bf16 v[52:55], v[204:207], v[212:215], v[52:55]
	v_mfma_f32_16x16x32_bf16 v[40:43], v[174:177], v[220:223], v[40:43]
	v_mfma_f32_16x16x32_bf16 v[36:39], v[204:207], v[220:223], v[36:39]
	v_mfma_f32_16x16x32_bf16 v[24:27], v[174:177], v[228:231], v[24:27]
	v_mfma_f32_16x16x32_bf16 v[20:23], v[204:207], v[228:231], v[20:23]
	v_mfma_f32_16x16x32_bf16 v[8:11], v[174:177], v[236:239], v[8:11]
	v_mfma_f32_16x16x32_bf16 v[4:7], v[204:207], v[236:239], v[4:7]
	s_setprio 3
	s_barrier
	s_add_i32 s64, 0, 0x18000
	s_add_i32 s65, 0, 0x1c000
	ds_read_b128 v[142:145], v247 offset:32768
	ds_read_b128 v[146:149], v247 offset:33792
	ds_read_b128 v[150:153], v247 offset:34816
	ds_read_b128 v[154:157], v247 offset:35840
	ds_read_b128 v[158:161], v247 offset:49152
	ds_read_b128 v[174:177], v247 offset:50176
	ds_read_b128 v[180:183], v247 offset:51200
	ds_read_b128 v[204:207], v247 offset:52224
	s_add_u32 s34, s40, 0x158000
	s_addc_u32 s35, s41, 0
	s_mov_b32 m0, s49
	ds_read_b128 v[208:211], v179 offset:32768
	ds_read_b128 v[212:215], v179 offset:33792
	ds_read_b128 v[216:219], v179 offset:34816
	ds_read_b128 v[220:223], v179 offset:35840
	ds_read_b128 v[224:227], v179 offset:36864
	ds_read_b128 v[228:231], v179 offset:37888
	ds_read_b128 v[232:235], v179 offset:38912
	ds_read_b128 v[236:239], v179 offset:39936
	global_load_lds_dwordx4 v2, s[34:35]
	s_mov_b32 m0, s50
	s_nop 0
	global_load_lds_dwordx4 v132, s[34:35]
	s_waitcnt vmcnt(8) lgkmcnt(0)
	s_barrier
; #define PG8_STAGE(bufoff, gbase, voff) do { _Pragma("unroll") for (int _i = 0; _i < 2; ++_i) \
;         __builtin_amdgcn_global_load_lds((const unsigned*)((const char*)(gbase) + (voff)[_i]), (PG8_LAS unsigned*)(lds + (bufoff) + ldsw + _i * 8192), 16, 0, 0); } while (0)
; #define PG8_LDA(dst, b, h) do { _Pragma("unroll") for (int m = 0; m < 4; ++m) _Pragma("unroll") for (int k = 0; k < 2; ++k) dst[m][k] = *(const PG8_LAS bf16x8*)(lds + PG8_SA(b, h) + aoff + m * 2048 + k * 1024); } while (0)
; #define PG8_MMA(ai, bj, At, Bt) do { __builtin_amdgcn_s_setprio(1); _Pragma("unroll") for (int m = 0; m < 4; ++m) _Pragma("unroll") for (int n = 0; n < 2; ++n) _Pragma("unroll") for (int k = 0; k < 2; ++k) \
;         acc[ai][bj][m][n] = __builtin_amdgcn_mfma_f32_16x16x32_bf16(Bt[n][k], At[m][k], acc[ai][bj][m][n], 0, 0, 0); __builtin_amdgcn_s_setprio(0); } while (0)
; #define PG8_WAIT_V(n) asm volatile("s_waitcnt vmcnt(" #n ")" ::: "memory")
; #define PG8_WAIT_L(n) asm volatile("s_waitcnt lgkmcnt(" #n ")" ::: "memory")
; #define PG8_BAR __builtin_amdgcn_s_barrier()
; #define PG8_SCHED __builtin_amdgcn_sched_barrier(0)
; template <class Epi, class Sched, bool ALIGN_EPI = false, bool SP2 = false>
; __device__ __forceinline__ void gemm_phase(PG8_LAS unsigned char* lds, const Gemm g, const Sched& S, const Epi& E) {
;     ...
;             PG8_WAIT_V(8); PG8_WAIT_L(0); PG8_BAR; PG8_MMA(0, 0, At, B0); PG8_MMA(0, 1, At, B1); PG8_BAR; PG8_SCHED;
;             PG8_LDA(At, 1, 1); PG8_STAGE(PG8_SB(1, 0), b3, voffB); PG8_STAGE(PG8_SB(1, 1), b3 + hstep, voffB); PG8_STAGE(PG8_SA(1, 0), a3, voffA);
;             PG8_WAIT_V(8); PG8_WAIT_L(0); PG8_BAR; PG8_MMA(1, 0, At, B0); PG8_MMA(1, 1, At, B1); PG8_BAR; PG8_SCHED;
	s_setprio 0
	s_waitcnt lgkmcnt(0)
	v_mfma_f32_16x16x32_bf16 v[128:131], v[142:145], v[208:211], v[128:131]
	v_mfma_f32_16x16x32_bf16 v[124:127], v[150:153], v[208:211], v[124:127]
	v_mfma_f32_16x16x32_bf16 v[112:115], v[142:145], v[216:219], v[112:115]
	v_mfma_f32_16x16x32_bf16 v[108:111], v[150:153], v[216:219], v[108:111]
	v_mfma_f32_16x16x32_bf16 v[96:99], v[142:145], v[224:227], v[96:99]
	v_mfma_f32_16x16x32_bf16 v[92:95], v[150:153], v[224:227], v[92:95]
	v_mfma_f32_16x16x32_bf16 v[80:83], v[142:145], v[232:235], v[80:83]
	v_mfma_f32_16x16x32_bf16 v[76:79], v[150:153], v[232:235], v[76:79]
	v_mfma_f32_16x16x32_bf16 v[128:131], v[146:149], v[212:215], v[128:131]
	v_mfma_f32_16x16x32_bf16 v[124:127], v[154:157], v[212:215], v[124:127]
	v_mfma_f32_16x16x32_bf16 v[112:115], v[146:149], v[220:223], v[112:115]
	v_mfma_f32_16x16x32_bf16 v[108:111], v[154:157], v[220:223], v[108:111]
	v_mfma_f32_16x16x32_bf16 v[96:99], v[146:149], v[228:231], v[96:99]
	v_mfma_f32_16x16x32_bf16 v[92:95], v[154:157], v[228:231], v[92:95]
	v_mfma_f32_16x16x32_bf16 v[80:83], v[146:149], v[236:239], v[80:83]
	v_mfma_f32_16x16x32_bf16 v[76:79], v[154:157], v[236:239], v[76:79]
	v_mfma_f32_16x16x32_bf16 v[120:123], v[158:161], v[208:211], v[120:123]
	v_mfma_f32_16x16x32_bf16 v[116:119], v[180:183], v[208:211], v[116:119]
	v_mfma_f32_16x16x32_bf16 v[104:107], v[158:161], v[216:219], v[104:107]
	v_mfma_f32_16x16x32_bf16 v[100:103], v[180:183], v[216:219], v[100:103]
	v_mfma_f32_16x16x32_bf16 v[88:91], v[158:161], v[224:227], v[88:91]
	v_mfma_f32_16x16x32_bf16 v[84:87], v[180:183], v[224:227], v[84:87]
	v_mfma_f32_16x16x32_bf16 v[72:75], v[158:161], v[232:235], v[72:75]
	v_mfma_f32_16x16x32_bf16 v[68:71], v[180:183], v[232:235], v[68:71]
	v_mfma_f32_16x16x32_bf16 v[120:123], v[174:177], v[212:215], v[120:123]
	v_mfma_f32_16x16x32_bf16 v[116:119], v[204:207], v[212:215], v[116:119]
	v_mfma_f32_16x16x32_bf16 v[104:107], v[174:177], v[220:223], v[104:107]
	v_mfma_f32_16x16x32_bf16 v[100:103], v[204:207], v[220:223], v[100:103]
	v_mfma_f32_16x16x32_bf16 v[88:91], v[174:177], v[228:231], v[88:91]
	v_mfma_f32_16x16x32_bf16 v[84:87], v[204:207], v[228:231], v[84:87]
	v_mfma_f32_16x16x32_bf16 v[72:75], v[174:177], v[236:239], v[72:75]
	v_mfma_f32_16x16x32_bf16 v[68:71], v[204:207], v[236:239], v[68:71]
	s_setprio 3
	s_barrier
	s_add_i32 s34, s64, s46
	s_add_i32 m0, s34, 0xffffff80
	ds_read_b128 v[208:211], v179 offset:49152
	ds_read_b128 v[212:215], v179 offset:50176
	ds_read_b128 v[216:219], v179 offset:51200
	ds_read_b128 v[220:223], v179 offset:52224
	ds_read_b128 v[224:227], v179 offset:53248
	ds_read_b128 v[228:231], v179 offset:54272
	ds_read_b128 v[232:235], v179 offset:55296
	ds_read_b128 v[236:239], v179 offset:56320
	global_load_lds_dwordx4 v2, s[38:39] offset:128
	s_add_i32 m0, s34, 0x1f80
	s_add_u32 s34, s38, 0x158080
	s_addc_u32 s35, s39, 0
	global_load_lds_dwordx4 v132, s[38:39] offset:128
	s_add_i32 s38, s65, s46
	s_mov_b32 m0, s38
	s_nop 0
	global_load_lds_dwordx4 v2, s[34:35]
	s_add_i32 m0, s38, 0x2000
	s_nop 0
	global_load_lds_dwordx4 v132, s[34:35]
	s_add_i32 m0, s53, 0xffffff80
	s_nop 0
	global_load_lds_dwordx4 v2, s[40:41] offset:128
	s_add_i32 m0, s54, 0xffffff80
	s_nop 0
	global_load_lds_dwordx4 v132, s[40:41] offset:128
	s_waitcnt vmcnt(8) lgkmcnt(0)
	s_barrier
	s_setprio 0
	s_waitcnt lgkmcnt(0)
	v_mfma_f32_16x16x32_bf16 v[64:67], v[142:145], v[208:211], v[64:67]
	v_mfma_f32_16x16x32_bf16 v[60:63], v[150:153], v[208:211], v[60:63]
	v_mfma_f32_16x16x32_bf16 v[48:51], v[142:145], v[216:219], v[48:51]
	v_mfma_f32_16x16x32_bf16 v[44:47], v[150:153], v[216:219], v[44:47]
	v_mfma_f32_16x16x32_bf16 v[32:35], v[142:145], v[224:227], v[32:35]
	v_mfma_f32_16x16x32_bf16 v[28:31], v[150:153], v[224:227], v[28:31]
	v_mfma_f32_16x16x32_bf16 v[16:19], v[142:145], v[232:235], v[16:19]
	v_mfma_f32_16x16x32_bf16 v[12:15], v[150:153], v[232:235], v[12:15]
	v_mfma_f32_16x16x32_bf16 v[64:67], v[146:149], v[212:215], v[64:67]
	v_mfma_f32_16x16x32_bf16 v[60:63], v[154:157], v[212:215], v[60:63]
	v_mfma_f32_16x16x32_bf16 v[48:51], v[146:149], v[220:223], v[48:51]
	v_mfma_f32_16x16x32_bf16 v[44:47], v[154:157], v[220:223], v[44:47]
	v_mfma_f32_16x16x32_bf16 v[32:35], v[146:149], v[228:231], v[32:35]
	v_mfma_f32_16x16x32_bf16 v[28:31], v[154:157], v[228:231], v[28:31]
	v_mfma_f32_16x16x32_bf16 v[16:19], v[146:149], v[236:239], v[16:19]
	v_mfma_f32_16x16x32_bf16 v[12:15], v[154:157], v[236:239], v[12:15]
	v_mfma_f32_16x16x32_bf16 v[56:59], v[158:161], v[208:211], v[56:59]
	v_mfma_f32_16x16x32_bf16 v[52:55], v[180:183], v[208:211], v[52:55]
	v_mfma_f32_16x16x32_bf16 v[40:43], v[158:161], v[216:219], v[40:43]
	v_mfma_f32_16x16x32_bf16 v[36:39], v[180:183], v[216:219], v[36:39]
	v_mfma_f32_16x16x32_bf16 v[24:27], v[158:161], v[224:227], v[24:27]
	v_mfma_f32_16x16x32_bf16 v[20:23], v[180:183], v[224:227], v[20:23]
	v_mfma_f32_16x16x32_bf16 v[8:11], v[158:161], v[232:235], v[8:11]
	v_mfma_f32_16x16x32_bf16 v[4:7], v[180:183], v[232:235], v[4:7]
	v_mfma_f32_16x16x32_bf16 v[56:59], v[174:177], v[212:215], v[56:59]
	v_mfma_f32_16x16x32_bf16 v[52:55], v[204:207], v[212:215], v[52:55]
	v_mfma_f32_16x16x32_bf16 v[40:43], v[174:177], v[220:223], v[40:43]
	v_mfma_f32_16x16x32_bf16 v[36:39], v[204:207], v[220:223], v[36:39]
	v_mfma_f32_16x16x32_bf16 v[24:27], v[174:177], v[228:231], v[24:27]
	v_mfma_f32_16x16x32_bf16 v[20:23], v[204:207], v[228:231], v[20:23]
	v_mfma_f32_16x16x32_bf16 v[8:11], v[174:177], v[236:239], v[8:11]
	v_mfma_f32_16x16x32_bf16 v[4:7], v[204:207], v[236:239], v[4:7]
	s_setprio 3
	s_barrier
	s_add_i32 s63, s63, 2
	s_add_u32 s61, s61, 0x100
	s_addc_u32 s62, s62, 0
	s_cmpk_gt_u32 s63, 0x53
	s_mov_b64 s[34:35], s[36:37]
	s_cbranch_scc0 .LBB0_575
	s_and_b64 vcc, exec, s[28:29]
	s_cbranch_vccz .LBB0_578
	s_barrier

; #define PG8_STAGE(bufoff, gbase, voff) do { _Pragma("unroll") for (int _i = 0; _i < 2; ++_i) \
;         __builtin_amdgcn_global_load_lds((const unsigned*)((const char*)(gbase) + (voff)[_i]), (PG8_LAS unsigned*)(lds + (bufoff) + ldsw + _i * 8192), 16, 0, 0); } while (0)
; #define PG8_LDA(dst, b, h) do { _Pragma("unroll") for (int m = 0; m < 4; ++m) _Pragma("unroll") for (int k = 0; k < 2; ++k) dst[m][k] = *(const PG8_LAS bf16x8*)(lds + PG8_SA(b, h) + aoff + m * 2048 + k * 1024); } while (0)
; #define PG8_LDB(dst, b, h) do { _Pragma("unroll") for (int n = 0; n < 2; ++n) _Pragma("unroll") for (int k = 0; k < 2; ++k) dst[n][k] = *(const PG8_LAS bf16x8*)(lds + PG8_SB(b, h) + boff + n * 2048 + k * 1024); } while (0)
; #define PG8_MMA(ai, bj, At, Bt) do { __builtin_amdgcn_s_setprio(1); _Pragma("unroll") for (int m = 0; m < 4; ++m) _Pragma("unroll") for (int n = 0; n < 2; ++n) _Pragma("unroll") for (int k = 0; k < 2; ++k) \
;         acc[ai][bj][m][n] = __builtin_amdgcn_mfma_f32_16x16x32_bf16(Bt[n][k], At[m][k], acc[ai][bj][m][n], 0, 0, 0); __builtin_amdgcn_s_setprio(0); } while (0)
; #define PG8_WAIT_V(n) asm volatile("s_waitcnt vmcnt(" #n ")" ::: "memory")
; template <class Epi, class Sched, bool ALIGN_EPI = false, bool SP2 = false>
; __device__ __forceinline__ void gemm_phase(PG8_LAS unsigned char* lds, const Gemm g, const Sched& S, const Epi& E) {
;     ...
;         for (int t = 0; t < nt; t += 2) {
;             const bool last = (t == nt - 2);
;             const char* a1 = cA + (size_t)(t + 1) * kstep;
;             const char* a2 = last ? nA : cA + (size_t)(t + 2) * kstep; const char* b2 = last ? nB : cB + (size_t)(t + 2) * kstep;
;             const char* a3 = a2 + kstep; const char* b3 = b2 + kstep;
;             if (last && has_next) S.a_ready(nxt);
;             if constexpr (SP2) {
;             PG8_LDB(B0, 0, 0); PG8_LDB(B1, 0, 1); PG8_SCHED; PG8_LDA(At, 0, 0); PG8_STAGE(PG8_SA(1, 1), a1 + hstep, voffA);
;             PG8_WAIT_V(8); PG8_WAIT_L(0); PG8_BAR; PG8_MMA(0, 0, At, B0); PG8_MMA(0, 1, At, B1); PG8_BAR; PG8_SCHED;
;     ...
;         if (zero_acc) {
; #pragma unroll
;         for (int a = 0; a < 2; ++a)
; #pragma unroll
;             for (int b = 0; b < 2; ++b)
; #pragma unroll
;                 for (int m = 0; m < 4; ++m)
; #pragma unroll
;                     for (int n = 0; n < 2; ++n) acc[a][b][m][n] = (f32x4){0.f, 0.f, 0.f, 0.f};
.LBB0_673:
	s_add_u32 s40, s40, 0x80080
	s_addc_u32 s41, s41, 0
	s_add_u32 s35, s42, 0x100
	v_mov_b32_e32 v4, 0
	s_addc_u32 s62, s43, 0
	s_mov_b32 s63, -2
	v_mov_b32_e32 v5, v4
	v_mov_b32_e32 v6, v4
	v_mov_b32_e32 v7, v4
	v_mov_b32_e32 v8, v4
	v_mov_b32_e32 v9, v4
	v_mov_b32_e32 v10, v4
	v_mov_b32_e32 v11, v4
	v_mov_b32_e32 v16, v4
	v_mov_b32_e32 v17, v4
	v_mov_b32_e32 v18, v4
	v_mov_b32_e32 v19, v4
	v_mov_b32_e32 v24, v4
	v_mov_b32_e32 v25, v4
	v_mov_b32_e32 v26, v4
	v_mov_b32_e32 v27, v4
	v_mov_b32_e32 v32, v4
	v_mov_b32_e32 v33, v4
	v_mov_b32_e32 v34, v4
	v_mov_b32_e32 v35, v4
	v_mov_b32_e32 v40, v4
	v_mov_b32_e32 v41, v4
	v_mov_b32_e32 v42, v4
	v_mov_b32_e32 v43, v4
	v_mov_b32_e32 v48, v4
	v_mov_b32_e32 v49, v4
	v_mov_b32_e32 v50, v4
	v_mov_b32_e32 v51, v4
	v_mov_b32_e32 v56, v4
	v_mov_b32_e32 v57, v4
	v_mov_b32_e32 v58, v4
	v_mov_b32_e32 v59, v4
	v_mov_b32_e32 v12, v4
	v_mov_b32_e32 v13, v4
	v_mov_b32_e32 v14, v4
	v_mov_b32_e32 v15, v4
	v_mov_b32_e32 v20, v4
	v_mov_b32_e32 v21, v4
	v_mov_b32_e32 v22, v4
	v_mov_b32_e32 v23, v4
	v_mov_b32_e32 v28, v4
	v_mov_b32_e32 v29, v4
	v_mov_b32_e32 v30, v4
	v_mov_b32_e32 v31, v4
	v_mov_b32_e32 v36, v4
	v_mov_b32_e32 v37, v4
	v_mov_b32_e32 v38, v4
	v_mov_b32_e32 v39, v4
	v_mov_b32_e32 v44, v4
	v_mov_b32_e32 v45, v4
	v_mov_b32_e32 v46, v4
	v_mov_b32_e32 v47, v4
	v_mov_b32_e32 v52, v4
	v_mov_b32_e32 v53, v4
	v_mov_b32_e32 v54, v4
	v_mov_b32_e32 v55, v4
	v_mov_b32_e32 v60, v4
	v_mov_b32_e32 v61, v4
	v_mov_b32_e32 v62, v4
	v_mov_b32_e32 v63, v4
	v_mov_b32_e32 v64, v4
	v_mov_b32_e32 v65, v4
	v_mov_b32_e32 v66, v4
	v_mov_b32_e32 v67, v4
	v_mov_b32_e32 v68, v4
	v_mov_b32_e32 v69, v4
	v_mov_b32_e32 v70, v4
	v_mov_b32_e32 v71, v4
	v_mov_b32_e32 v72, v4
	v_mov_b32_e32 v73, v4
	v_mov_b32_e32 v74, v4
	v_mov_b32_e32 v75, v4
	v_mov_b32_e32 v80, v4
	v_mov_b32_e32 v81, v4
	v_mov_b32_e32 v82, v4
	v_mov_b32_e32 v83, v4
	v_mov_b32_e32 v88, v4
	v_mov_b32_e32 v89, v4
	v_mov_b32_e32 v90, v4
	v_mov_b32_e32 v91, v4
	v_mov_b32_e32 v96, v4
	v_mov_b32_e32 v97, v4
	v_mov_b32_e32 v98, v4
	v_mov_b32_e32 v99, v4
	v_mov_b32_e32 v104, v4
	v_mov_b32_e32 v105, v4
	v_mov_b32_e32 v106, v4
	v_mov_b32_e32 v107, v4
	v_mov_b32_e32 v112, v4
	v_mov_b32_e32 v113, v4
	v_mov_b32_e32 v114, v4
	v_mov_b32_e32 v115, v4
	v_mov_b32_e32 v120, v4
	v_mov_b32_e32 v121, v4
	v_mov_b32_e32 v122, v4
	v_mov_b32_e32 v123, v4
	v_mov_b32_e32 v76, v4
	v_mov_b32_e32 v77, v4
	v_mov_b32_e32 v78, v4
	v_mov_b32_e32 v79, v4
	v_mov_b32_e32 v84, v4
	v_mov_b32_e32 v85, v4
	v_mov_b32_e32 v86, v4
	v_mov_b32_e32 v87, v4
	v_mov_b32_e32 v92, v4
	v_mov_b32_e32 v93, v4
	v_mov_b32_e32 v94, v4
	v_mov_b32_e32 v95, v4
	v_mov_b32_e32 v100, v4
	v_mov_b32_e32 v101, v4
	v_mov_b32_e32 v102, v4
	v_mov_b32_e32 v103, v4
	v_mov_b32_e32 v108, v4
	v_mov_b32_e32 v109, v4
	v_mov_b32_e32 v110, v4
	v_mov_b32_e32 v111, v4
	v_mov_b32_e32 v116, v4
	v_mov_b32_e32 v117, v4
	v_mov_b32_e32 v118, v4
	v_mov_b32_e32 v119, v4
	v_mov_b32_e32 v124, v4
	v_mov_b32_e32 v125, v4
	v_mov_b32_e32 v126, v4
	v_mov_b32_e32 v127, v4
	v_mov_b32_e32 v128, v4
	v_mov_b32_e32 v129, v4
	v_mov_b32_e32 v130, v4
	v_mov_b32_e32 v131, v4
	v_add_u32_e32 v249, 0x10000, v173
	.p2align 6
	s_nop 0
.LBB0_674:
	s_add_u32 s42, s40, 0xfff80080
	s_addc_u32 s43, s41, -1
	s_add_i32 s64, 0, 0x10000
	s_cmp_eq_u32 s63, 28
	s_cselect_b32 s45, s5, s43
	s_cselect_b32 s44, s4, s42
	s_cselect_b32 s43, s37, s62
	s_cselect_b32 s42, s36, s35
	s_add_i32 s66, 0, 0x14000
	ds_read_b128 v[132:135], v249
	ds_read_b128 v[136:139], v249 offset:1024
	ds_read_b128 v[140:143], v249 offset:2048
	ds_read_b128 v[144:147], v249 offset:3072
	ds_read_b128 v[158:161], v249 offset:16384
	ds_read_b128 v[174:177], v249 offset:17408
	ds_read_b128 v[206:209], v249 offset:18432
	ds_read_b128 v[210:213], v249 offset:19456
	s_add_i32 m0, s39, 0xc000
	ds_read_b128 v[214:217], v204
	ds_read_b128 v[218:221], v204 offset:1024
	ds_read_b128 v[222:225], v204 offset:2048
	ds_read_b128 v[226:229], v204 offset:3072
	ds_read_b128 v[230:233], v204 offset:4096
	ds_read_b128 v[234:237], v204 offset:5120
	ds_read_b128 v[238:241], v204 offset:6144
	ds_read_b128 v[242:245], v204 offset:7168
	global_load_lds_dwordx4 v154, s[40:41]
	s_add_i32 m0, s39, 0xe000
	s_nop 0
	global_load_lds_dwordx4 v156, s[40:41]
	s_nop 0
	s_waitcnt vmcnt(8) lgkmcnt(0)
	s_barrier
	s_setprio 0
	s_waitcnt lgkmcnt(0)
	v_mfma_f32_16x16x32_bf16 v[128:131], v[132:135], v[214:217], v[128:131]
	v_mfma_f32_16x16x32_bf16 v[124:127], v[140:143], v[214:217], v[124:127]
	v_mfma_f32_16x16x32_bf16 v[116:119], v[132:135], v[222:225], v[116:119]
	v_mfma_f32_16x16x32_bf16 v[108:111], v[140:143], v[222:225], v[108:111]
	v_mfma_f32_16x16x32_bf16 v[100:103], v[132:135], v[230:233], v[100:103]
	v_mfma_f32_16x16x32_bf16 v[92:95], v[140:143], v[230:233], v[92:95]
	v_mfma_f32_16x16x32_bf16 v[84:87], v[132:135], v[238:241], v[84:87]
	v_mfma_f32_16x16x32_bf16 v[76:79], v[140:143], v[238:241], v[76:79]
	v_mfma_f32_16x16x32_bf16 v[128:131], v[136:139], v[218:221], v[128:131]
	v_mfma_f32_16x16x32_bf16 v[124:127], v[144:147], v[218:221], v[124:127]
	v_mfma_f32_16x16x32_bf16 v[116:119], v[136:139], v[226:229], v[116:119]
	v_mfma_f32_16x16x32_bf16 v[108:111], v[144:147], v[226:229], v[108:111]
	v_mfma_f32_16x16x32_bf16 v[100:103], v[136:139], v[234:237], v[100:103]
	v_mfma_f32_16x16x32_bf16 v[92:95], v[144:147], v[234:237], v[92:95]
	v_mfma_f32_16x16x32_bf16 v[84:87], v[136:139], v[242:245], v[84:87]
	v_mfma_f32_16x16x32_bf16 v[76:79], v[144:147], v[242:245], v[76:79]
	v_mfma_f32_16x16x32_bf16 v[120:123], v[158:161], v[214:217], v[120:123]
	v_mfma_f32_16x16x32_bf16 v[112:115], v[206:209], v[214:217], v[112:115]
	v_mfma_f32_16x16x32_bf16 v[104:107], v[158:161], v[222:225], v[104:107]
	v_mfma_f32_16x16x32_bf16 v[96:99], v[206:209], v[222:225], v[96:99]
	v_mfma_f32_16x16x32_bf16 v[88:91], v[158:161], v[230:233], v[88:91]
	v_mfma_f32_16x16x32_bf16 v[80:83], v[206:209], v[230:233], v[80:83]
	v_mfma_f32_16x16x32_bf16 v[72:75], v[158:161], v[238:241], v[72:75]
	v_mfma_f32_16x16x32_bf16 v[68:71], v[206:209], v[238:241], v[68:71]
	v_mfma_f32_16x16x32_bf16 v[120:123], v[174:177], v[218:221], v[120:123]
	v_mfma_f32_16x16x32_bf16 v[112:115], v[210:213], v[218:221], v[112:115]
	v_mfma_f32_16x16x32_bf16 v[104:107], v[174:177], v[226:229], v[104:107]
	v_mfma_f32_16x16x32_bf16 v[96:99], v[210:213], v[226:229], v[96:99]
	v_mfma_f32_16x16x32_bf16 v[88:91], v[174:177], v[234:237], v[88:91]
	v_mfma_f32_16x16x32_bf16 v[80:83], v[210:213], v[234:237], v[80:83]
	v_mfma_f32_16x16x32_bf16 v[72:75], v[174:177], v[242:245], v[72:75]
	v_mfma_f32_16x16x32_bf16 v[68:71], v[210:213], v[242:245], v[68:71]
	s_setprio 3
	s_barrier
; #define PG8_STAGE(bufoff, gbase, voff) do { _Pragma("unroll") for (int _i = 0; _i < 2; ++_i) \
;         __builtin_amdgcn_global_load_lds((const unsigned*)((const char*)(gbase) + (voff)[_i]), (PG8_LAS unsigned*)(lds + (bufoff) + ldsw + _i * 8192), 16, 0, 0); } while (0)
; #define PG8_LDA(dst, b, h) do { _Pragma("unroll") for (int m = 0; m < 4; ++m) _Pragma("unroll") for (int k = 0; k < 2; ++k) dst[m][k] = *(const PG8_LAS bf16x8*)(lds + PG8_SA(b, h) + aoff + m * 2048 + k * 1024); } while (0)
; #define PG8_LDB(dst, b, h) do { _Pragma("unroll") for (int n = 0; n < 2; ++n) _Pragma("unroll") for (int k = 0; k < 2; ++k) dst[n][k] = *(const PG8_LAS bf16x8*)(lds + PG8_SB(b, h) + boff + n * 2048 + k * 1024); } while (0)
; #define PG8_MMA(ai, bj, At, Bt) do { __builtin_amdgcn_s_setprio(1); _Pragma("unroll") for (int m = 0; m < 4; ++m) _Pragma("unroll") for (int n = 0; n < 2; ++n) _Pragma("unroll") for (int k = 0; k < 2; ++k) \
;         acc[ai][bj][m][n] = __builtin_amdgcn_mfma_f32_16x16x32_bf16(Bt[n][k], At[m][k], acc[ai][bj][m][n], 0, 0, 0); __builtin_amdgcn_s_setprio(0); } while (0)
; #define PG8_WAIT_V(n) asm volatile("s_waitcnt vmcnt(" #n ")" ::: "memory")
; #define PG8_WAIT_L(n) asm volatile("s_waitcnt lgkmcnt(" #n ")" ::: "memory")
; #define PG8_BAR __builtin_amdgcn_s_barrier()
; #define PG8_SCHED __builtin_amdgcn_sched_barrier(0)
; template <class Epi, class Sched, bool ALIGN_EPI = false, bool SP2 = false>
; __device__ __forceinline__ void gemm_phase(PG8_LAS unsigned char* lds, const Gemm g, const Sched& S, const Epi& E) {
;     ...
;             PG8_LDA(At, 0, 1); PG8_STAGE(PG8_SB(0, 0), b2, voffB); PG8_STAGE(PG8_SB(0, 1), b2 + hstep, voffB); PG8_STAGE(PG8_SA(0, 0), a2, voffA);
;             PG8_WAIT_V(8); PG8_WAIT_L(0); PG8_BAR; PG8_MMA(1, 0, At, B0); PG8_MMA(1, 1, At, B1); PG8_BAR; PG8_SCHED;
;             PG8_LDB(B0, 1, 0); PG8_LDB(B1, 1, 1); PG8_SCHED; PG8_LDA(At, 1, 0); PG8_STAGE(PG8_SA(0, 1), a2 + hstep, voffA);
;             PG8_WAIT_V(8); PG8_WAIT_L(0); PG8_BAR; PG8_MMA(0, 0, At, B0); PG8_MMA(0, 1, At, B1); PG8_BAR; PG8_SCHED;
	s_add_i32 s64, s64, s46
	s_mov_b32 m0, s64
	ds_read_b128 v[214:217], v204 offset:16384
	ds_read_b128 v[218:221], v204 offset:17408
	ds_read_b128 v[222:225], v204 offset:18432
	ds_read_b128 v[226:229], v204 offset:19456
	ds_read_b128 v[230:233], v204 offset:20480
	ds_read_b128 v[234:237], v204 offset:21504
	ds_read_b128 v[238:241], v204 offset:22528
	ds_read_b128 v[242:245], v204 offset:23552
	global_load_lds_dwordx4 v2, s[42:43]
	s_add_i32 m0, s64, 0x2000
	s_add_u32 s64, s42, 0x80000
	s_addc_u32 s65, s43, 0
	s_add_i32 s66, s66, s46
	global_load_lds_dwordx4 v148, s[42:43]
	s_mov_b32 m0, s66
	s_nop 0
	global_load_lds_dwordx4 v2, s[64:65]
	s_add_i32 m0, s66, 0x2000
	s_nop 0
	global_load_lds_dwordx4 v148, s[64:65]
	s_mov_b32 m0, s39
	s_nop 0
	global_load_lds_dwordx4 v152, s[44:45]
	s_mov_b32 m0, s51
	s_nop 0
	global_load_lds_dwordx4 v150, s[44:45]
	s_nop 0
	s_waitcnt vmcnt(8) lgkmcnt(0)
	s_barrier
	s_setprio 0
	s_waitcnt lgkmcnt(0)
	v_mfma_f32_16x16x32_bf16 v[64:67], v[132:135], v[214:217], v[64:67]
	v_mfma_f32_16x16x32_bf16 v[60:63], v[140:143], v[214:217], v[60:63]
	v_mfma_f32_16x16x32_bf16 v[52:55], v[132:135], v[222:225], v[52:55]
	v_mfma_f32_16x16x32_bf16 v[44:47], v[140:143], v[222:225], v[44:47]
	v_mfma_f32_16x16x32_bf16 v[36:39], v[132:135], v[230:233], v[36:39]
	v_mfma_f32_16x16x32_bf16 v[28:31], v[140:143], v[230:233], v[28:31]
	v_mfma_f32_16x16x32_bf16 v[20:23], v[132:135], v[238:241], v[20:23]
	v_mfma_f32_16x16x32_bf16 v[12:15], v[140:143], v[238:241], v[12:15]
	v_mfma_f32_16x16x32_bf16 v[64:67], v[136:139], v[218:221], v[64:67]
	v_mfma_f32_16x16x32_bf16 v[60:63], v[144:147], v[218:221], v[60:63]
	v_mfma_f32_16x16x32_bf16 v[52:55], v[136:139], v[226:229], v[52:55]
	v_mfma_f32_16x16x32_bf16 v[44:47], v[144:147], v[226:229], v[44:47]
	v_mfma_f32_16x16x32_bf16 v[36:39], v[136:139], v[234:237], v[36:39]
	v_mfma_f32_16x16x32_bf16 v[28:31], v[144:147], v[234:237], v[28:31]
	v_mfma_f32_16x16x32_bf16 v[20:23], v[136:139], v[242:245], v[20:23]
	v_mfma_f32_16x16x32_bf16 v[12:15], v[144:147], v[242:245], v[12:15]
	v_mfma_f32_16x16x32_bf16 v[56:59], v[158:161], v[214:217], v[56:59]
	v_mfma_f32_16x16x32_bf16 v[48:51], v[206:209], v[214:217], v[48:51]
	v_mfma_f32_16x16x32_bf16 v[40:43], v[158:161], v[222:225], v[40:43]
	v_mfma_f32_16x16x32_bf16 v[32:35], v[206:209], v[222:225], v[32:35]
	v_mfma_f32_16x16x32_bf16 v[24:27], v[158:161], v[230:233], v[24:27]
	v_mfma_f32_16x16x32_bf16 v[16:19], v[206:209], v[230:233], v[16:19]
	v_mfma_f32_16x16x32_bf16 v[8:11], v[158:161], v[238:241], v[8:11]
	v_mfma_f32_16x16x32_bf16 v[4:7], v[206:209], v[238:241], v[4:7]
	v_mfma_f32_16x16x32_bf16 v[56:59], v[174:177], v[218:221], v[56:59]
	v_mfma_f32_16x16x32_bf16 v[48:51], v[210:213], v[218:221], v[48:51]
	v_mfma_f32_16x16x32_bf16 v[40:43], v[174:177], v[226:229], v[40:43]
	v_mfma_f32_16x16x32_bf16 v[32:35], v[210:213], v[226:229], v[32:35]
	v_mfma_f32_16x16x32_bf16 v[24:27], v[174:177], v[234:237], v[24:27]
	v_mfma_f32_16x16x32_bf16 v[16:19], v[210:213], v[234:237], v[16:19]
	v_mfma_f32_16x16x32_bf16 v[8:11], v[174:177], v[242:245], v[8:11]
	v_mfma_f32_16x16x32_bf16 v[4:7], v[210:213], v[242:245], v[4:7]
	s_setprio 3
	s_barrier
	s_add_i32 s64, 0, 0x18000
	s_add_i32 s65, 0, 0x1c000
	ds_read_b128 v[132:135], v249 offset:32768
	ds_read_b128 v[136:139], v249 offset:33792
	ds_read_b128 v[140:143], v249 offset:34816
	ds_read_b128 v[144:147], v249 offset:35840
	ds_read_b128 v[158:161], v249 offset:49152
	ds_read_b128 v[174:177], v249 offset:50176
	ds_read_b128 v[206:209], v249 offset:51200
	ds_read_b128 v[210:213], v249 offset:52224
	s_add_u32 s100, s44, 0x80
	s_addc_u32 s101, s45, 0
	s_add_u32 s44, s44, 0x80000
	s_addc_u32 s45, s45, 0
	s_mov_b32 m0, s52
	ds_read_b128 v[214:217], v204 offset:32768
	ds_read_b128 v[218:221], v204 offset:33792
	ds_read_b128 v[222:225], v204 offset:34816
	ds_read_b128 v[226:229], v204 offset:35840
	ds_read_b128 v[230:233], v204 offset:36864
	ds_read_b128 v[234:237], v204 offset:37888
	ds_read_b128 v[238:241], v204 offset:38912
	ds_read_b128 v[242:245], v204 offset:39936
	global_load_lds_dwordx4 v152, s[44:45]
	s_mov_b32 m0, s53
	s_nop 0
	global_load_lds_dwordx4 v150, s[44:45]
	s_nop 0
	s_waitcnt vmcnt(8) lgkmcnt(0)
	s_barrier
; #define PG8_STAGE(bufoff, gbase, voff) do { _Pragma("unroll") for (int _i = 0; _i < 2; ++_i) \
;         __builtin_amdgcn_global_load_lds((const unsigned*)((const char*)(gbase) + (voff)[_i]), (PG8_LAS unsigned*)(lds + (bufoff) + ldsw + _i * 8192), 16, 0, 0); } while (0)
; #define PG8_LDA(dst, b, h) do { _Pragma("unroll") for (int m = 0; m < 4; ++m) _Pragma("unroll") for (int k = 0; k < 2; ++k) dst[m][k] = *(const PG8_LAS bf16x8*)(lds + PG8_SA(b, h) + aoff + m * 2048 + k * 1024); } while (0)
; #define PG8_MMA(ai, bj, At, Bt) do { __builtin_amdgcn_s_setprio(1); _Pragma("unroll") for (int m = 0; m < 4; ++m) _Pragma("unroll") for (int n = 0; n < 2; ++n) _Pragma("unroll") for (int k = 0; k < 2; ++k) \
;         acc[ai][bj][m][n] = __builtin_amdgcn_mfma_f32_16x16x32_bf16(Bt[n][k], At[m][k], acc[ai][bj][m][n], 0, 0, 0); __builtin_amdgcn_s_setprio(0); } while (0)
; #define PG8_WAIT_V(n) asm volatile("s_waitcnt vmcnt(" #n ")" ::: "memory")
; #define PG8_WAIT_L(n) asm volatile("s_waitcnt lgkmcnt(" #n ")" ::: "memory")
; #define PG8_BAR __builtin_amdgcn_s_barrier()
; #define PG8_SCHED __builtin_amdgcn_sched_barrier(0)
; template <class Epi, class Sched, bool ALIGN_EPI = false, bool SP2 = false>
; __device__ __forceinline__ void gemm_phase(PG8_LAS unsigned char* lds, const Gemm g, const Sched& S, const Epi& E) {
;     ...
;             PG8_WAIT_V(8); PG8_WAIT_L(0); PG8_BAR; PG8_MMA(0, 0, At, B0); PG8_MMA(0, 1, At, B1); PG8_BAR; PG8_SCHED;
;             PG8_LDA(At, 1, 1); PG8_STAGE(PG8_SB(1, 0), b3, voffB); PG8_STAGE(PG8_SB(1, 1), b3 + hstep, voffB); PG8_STAGE(PG8_SA(1, 0), a3, voffA);
;             PG8_WAIT_V(8); PG8_WAIT_L(0); PG8_BAR; PG8_MMA(1, 0, At, B0); PG8_MMA(1, 1, At, B1); PG8_BAR; PG8_SCHED;
	s_setprio 0
	s_waitcnt lgkmcnt(0)
	v_mfma_f32_16x16x32_bf16 v[128:131], v[132:135], v[214:217], v[128:131]
	v_mfma_f32_16x16x32_bf16 v[124:127], v[140:143], v[214:217], v[124:127]
	v_mfma_f32_16x16x32_bf16 v[116:119], v[132:135], v[222:225], v[116:119]
	v_mfma_f32_16x16x32_bf16 v[108:111], v[140:143], v[222:225], v[108:111]
	v_mfma_f32_16x16x32_bf16 v[100:103], v[132:135], v[230:233], v[100:103]
	v_mfma_f32_16x16x32_bf16 v[92:95], v[140:143], v[230:233], v[92:95]
	v_mfma_f32_16x16x32_bf16 v[84:87], v[132:135], v[238:241], v[84:87]
	v_mfma_f32_16x16x32_bf16 v[76:79], v[140:143], v[238:241], v[76:79]
	v_mfma_f32_16x16x32_bf16 v[128:131], v[136:139], v[218:221], v[128:131]
	v_mfma_f32_16x16x32_bf16 v[124:127], v[144:147], v[218:221], v[124:127]
	v_mfma_f32_16x16x32_bf16 v[116:119], v[136:139], v[226:229], v[116:119]
	v_mfma_f32_16x16x32_bf16 v[108:111], v[144:147], v[226:229], v[108:111]
	v_mfma_f32_16x16x32_bf16 v[100:103], v[136:139], v[234:237], v[100:103]
	v_mfma_f32_16x16x32_bf16 v[92:95], v[144:147], v[234:237], v[92:95]
	v_mfma_f32_16x16x32_bf16 v[84:87], v[136:139], v[242:245], v[84:87]
	v_mfma_f32_16x16x32_bf16 v[76:79], v[144:147], v[242:245], v[76:79]
	v_mfma_f32_16x16x32_bf16 v[120:123], v[158:161], v[214:217], v[120:123]
	v_mfma_f32_16x16x32_bf16 v[112:115], v[206:209], v[214:217], v[112:115]
	v_mfma_f32_16x16x32_bf16 v[104:107], v[158:161], v[222:225], v[104:107]
	v_mfma_f32_16x16x32_bf16 v[96:99], v[206:209], v[222:225], v[96:99]
	v_mfma_f32_16x16x32_bf16 v[88:91], v[158:161], v[230:233], v[88:91]
	v_mfma_f32_16x16x32_bf16 v[80:83], v[206:209], v[230:233], v[80:83]
	v_mfma_f32_16x16x32_bf16 v[72:75], v[158:161], v[238:241], v[72:75]
	v_mfma_f32_16x16x32_bf16 v[68:71], v[206:209], v[238:241], v[68:71]
	v_mfma_f32_16x16x32_bf16 v[120:123], v[174:177], v[218:221], v[120:123]
	v_mfma_f32_16x16x32_bf16 v[112:115], v[210:213], v[218:221], v[112:115]
	v_mfma_f32_16x16x32_bf16 v[104:107], v[174:177], v[226:229], v[104:107]
	v_mfma_f32_16x16x32_bf16 v[96:99], v[210:213], v[226:229], v[96:99]
	v_mfma_f32_16x16x32_bf16 v[88:91], v[174:177], v[234:237], v[88:91]
	v_mfma_f32_16x16x32_bf16 v[80:83], v[210:213], v[234:237], v[80:83]
	v_mfma_f32_16x16x32_bf16 v[72:75], v[174:177], v[242:245], v[72:75]
	v_mfma_f32_16x16x32_bf16 v[68:71], v[210:213], v[242:245], v[68:71]
	s_setprio 3
	s_barrier
	s_add_i32 s44, s64, s46
	s_add_i32 m0, s44, 0xffffff80
	ds_read_b128 v[214:217], v204 offset:49152
	ds_read_b128 v[218:221], v204 offset:50176
	ds_read_b128 v[222:225], v204 offset:51200
	ds_read_b128 v[226:229], v204 offset:52224
	ds_read_b128 v[230:233], v204 offset:53248
	ds_read_b128 v[234:237], v204 offset:54272
	ds_read_b128 v[238:241], v204 offset:55296
	ds_read_b128 v[242:245], v204 offset:56320
	global_load_lds_dwordx4 v2, s[42:43] offset:128
	s_add_i32 m0, s44, 0x1f80
	s_add_i32 s44, s65, s46
	global_load_lds_dwordx4 v148, s[42:43] offset:128
	s_add_u32 s42, s42, 0x80080
	s_addc_u32 s43, s43, 0
	s_mov_b32 m0, s44
	s_nop 0
	global_load_lds_dwordx4 v2, s[42:43]
	s_add_i32 m0, s44, 0x2000
	s_nop 0
	global_load_lds_dwordx4 v148, s[42:43]
	s_mov_b32 m0, s54
	s_nop 0
	global_load_lds_dwordx4 v152, s[100:101]
	s_mov_b32 m0, s55
	s_nop 0
	global_load_lds_dwordx4 v150, s[100:101]
	s_waitcnt vmcnt(8) lgkmcnt(0)
	s_barrier
	s_setprio 0
	s_waitcnt lgkmcnt(0)
	v_mfma_f32_16x16x32_bf16 v[64:67], v[132:135], v[214:217], v[64:67]
	v_mfma_f32_16x16x32_bf16 v[60:63], v[140:143], v[214:217], v[60:63]
	v_mfma_f32_16x16x32_bf16 v[52:55], v[132:135], v[222:225], v[52:55]
	v_mfma_f32_16x16x32_bf16 v[44:47], v[140:143], v[222:225], v[44:47]
	v_mfma_f32_16x16x32_bf16 v[36:39], v[132:135], v[230:233], v[36:39]
	v_mfma_f32_16x16x32_bf16 v[28:31], v[140:143], v[230:233], v[28:31]
	v_mfma_f32_16x16x32_bf16 v[20:23], v[132:135], v[238:241], v[20:23]
	v_mfma_f32_16x16x32_bf16 v[12:15], v[140:143], v[238:241], v[12:15]
	v_mfma_f32_16x16x32_bf16 v[64:67], v[136:139], v[218:221], v[64:67]
	v_mfma_f32_16x16x32_bf16 v[60:63], v[144:147], v[218:221], v[60:63]
	v_mfma_f32_16x16x32_bf16 v[52:55], v[136:139], v[226:229], v[52:55]
	v_mfma_f32_16x16x32_bf16 v[44:47], v[144:147], v[226:229], v[44:47]
	v_mfma_f32_16x16x32_bf16 v[36:39], v[136:139], v[234:237], v[36:39]
	v_mfma_f32_16x16x32_bf16 v[28:31], v[144:147], v[234:237], v[28:31]
	v_mfma_f32_16x16x32_bf16 v[20:23], v[136:139], v[242:245], v[20:23]
	v_mfma_f32_16x16x32_bf16 v[12:15], v[144:147], v[242:245], v[12:15]
	v_mfma_f32_16x16x32_bf16 v[56:59], v[158:161], v[214:217], v[56:59]
	v_mfma_f32_16x16x32_bf16 v[48:51], v[206:209], v[214:217], v[48:51]
	v_mfma_f32_16x16x32_bf16 v[40:43], v[158:161], v[222:225], v[40:43]
	v_mfma_f32_16x16x32_bf16 v[32:35], v[206:209], v[222:225], v[32:35]
	v_mfma_f32_16x16x32_bf16 v[24:27], v[158:161], v[230:233], v[24:27]
	v_mfma_f32_16x16x32_bf16 v[16:19], v[206:209], v[230:233], v[16:19]
	v_mfma_f32_16x16x32_bf16 v[8:11], v[158:161], v[238:241], v[8:11]
	v_mfma_f32_16x16x32_bf16 v[4:7], v[206:209], v[238:241], v[4:7]
	v_mfma_f32_16x16x32_bf16 v[56:59], v[174:177], v[218:221], v[56:59]
	v_mfma_f32_16x16x32_bf16 v[48:51], v[210:213], v[218:221], v[48:51]
	v_mfma_f32_16x16x32_bf16 v[40:43], v[174:177], v[226:229], v[40:43]
	v_mfma_f32_16x16x32_bf16 v[32:35], v[210:213], v[226:229], v[32:35]
	v_mfma_f32_16x16x32_bf16 v[24:27], v[174:177], v[234:237], v[24:27]
	v_mfma_f32_16x16x32_bf16 v[16:19], v[210:213], v[234:237], v[16:19]
	v_mfma_f32_16x16x32_bf16 v[8:11], v[174:177], v[242:245], v[8:11]
	v_mfma_f32_16x16x32_bf16 v[4:7], v[210:213], v[242:245], v[4:7]
	s_setprio 3
	s_barrier
	s_add_i32 s63, s63, 2
	s_add_u32 s40, s40, 0x100
	s_addc_u32 s41, s41, 0
	s_add_u32 s35, s35, 0x100
	s_addc_u32 s62, s62, 0
	s_cmp_gt_u32 s63, 29
	s_cbranch_scc0 .LBB0_674
	s_and_b64 vcc, exec, s[30:31]
	s_cbranch_vccz .LBB0_677
	s_barrier

; #define PG8_STAGE(bufoff, gbase, voff) do { _Pragma("unroll") for (int _i = 0; _i < 2; ++_i) \
;         __builtin_amdgcn_global_load_lds((const unsigned*)((const char*)(gbase) + (voff)[_i]), (PG8_LAS unsigned*)(lds + (bufoff) + ldsw + _i * 8192), 16, 0, 0); } while (0)
; #define PG8_LDA(dst, b, h) do { _Pragma("unroll") for (int m = 0; m < 4; ++m) _Pragma("unroll") for (int k = 0; k < 2; ++k) dst[m][k] = *(const PG8_LAS bf16x8*)(lds + PG8_SA(b, h) + aoff + m * 2048 + k * 1024); } while (0)
; #define PG8_LDB(dst, b, h) do { _Pragma("unroll") for (int n = 0; n < 2; ++n) _Pragma("unroll") for (int k = 0; k < 2; ++k) dst[n][k] = *(const PG8_LAS bf16x8*)(lds + PG8_SB(b, h) + boff + n * 2048 + k * 1024); } while (0)
; #define PG8_MMA(ai, bj, At, Bt) do { __builtin_amdgcn_s_setprio(1); _Pragma("unroll") for (int m = 0; m < 4; ++m) _Pragma("unroll") for (int n = 0; n < 2; ++n) _Pragma("unroll") for (int k = 0; k < 2; ++k) \
;         acc[ai][bj][m][n] = __builtin_amdgcn_mfma_f32_16x16x32_bf16(Bt[n][k], At[m][k], acc[ai][bj][m][n], 0, 0, 0); __builtin_amdgcn_s_setprio(0); } while (0)
; #define PG8_WAIT_V(n) asm volatile("s_waitcnt vmcnt(" #n ")" ::: "memory")
; #define PG8_WAIT_L(n) asm volatile("s_waitcnt lgkmcnt(" #n ")" ::: "memory")
; #define PG8_BAR __builtin_amdgcn_s_barrier()
; #define PG8_SCHED __builtin_amdgcn_sched_barrier(0)
; template <class Epi, class Sched, bool ALIGN_EPI = false, bool SP2 = false>
; __device__ __forceinline__ void gemm_phase(PG8_LAS unsigned char* lds, const Gemm g, const Sched& S, const Epi& E) {
;     ...
;         for (int t = 0; t < nt; t += 2) {
;             const bool last = (t == nt - 2);
;             const char* a1 = cA + (size_t)(t + 1) * kstep;
;             const char* a2 = last ? nA : cA + (size_t)(t + 2) * kstep; const char* b2 = last ? nB : cB + (size_t)(t + 2) * kstep;
;             const char* a3 = a2 + kstep; const char* b3 = b2 + kstep;
;             if (last && has_next) S.a_ready(nxt);
;             if constexpr (SP2) {
;             PG8_LDB(B0, 0, 0); PG8_LDB(B1, 0, 1); PG8_SCHED; PG8_LDA(At, 0, 0); PG8_STAGE(PG8_SA(1, 1), a1 + hstep, voffA);
;             PG8_WAIT_V(8); PG8_WAIT_L(0); PG8_BAR; PG8_MMA(0, 0, At, B0); PG8_MMA(0, 1, At, B1); PG8_BAR; PG8_SCHED;
.LBB0_2095:
	s_add_u32 s40, s40, 0x40080
	s_addc_u32 s41, s41, 0
	s_add_u32 s11, s42, 0x100
	s_addc_u32 s13, s43, 0
	s_mov_b32 s26, -2
	v_add_u32_e32 v175, 0x10000, v173
	.p2align 6
	s_nop 0
.LBB0_2096:
	s_add_u32 s27, s40, 0xfffc0080
	s_addc_u32 s29, s41, -1
	s_add_i32 s31, 0, 0x10000
	s_cmp_eq_u32 s26, 12
	s_cselect_b32 s45, s1, s29
	s_cselect_b32 s44, s0, s27
	s_cselect_b32 s43, s35, s13
	s_cselect_b32 s42, s34, s11
	s_add_i32 s27, 0, 0x14000
	ds_read_b128 v[134:137], v175
	ds_read_b128 v[138:141], v175 offset:1024
	ds_read_b128 v[154:157], v175 offset:2048
	ds_read_b128 v[158:161], v175 offset:3072
	ds_read_b128 v[178:181], v175 offset:16384
	ds_read_b128 v[204:207], v175 offset:17408
	ds_read_b128 v[208:211], v175 offset:18432
	ds_read_b128 v[212:215], v175 offset:19456
	s_add_i32 m0, s55, 0xc000
	ds_read_b128 v[216:219], v177
	ds_read_b128 v[220:223], v177 offset:1024
	ds_read_b128 v[224:227], v177 offset:2048
	ds_read_b128 v[228:231], v177 offset:3072
	ds_read_b128 v[232:235], v177 offset:4096
	ds_read_b128 v[236:239], v177 offset:5120
	ds_read_b128 v[240:243], v177 offset:6144
	ds_read_b128 v[244:247], v177 offset:7168
	global_load_lds_dwordx4 v150, s[40:41]
	s_add_i32 m0, s55, 0xe000
	s_nop 0
	global_load_lds_dwordx4 v152, s[40:41]
	s_nop 0
	s_waitcnt vmcnt(8) lgkmcnt(0)
	s_barrier
	s_setprio 0
	s_waitcnt lgkmcnt(0)
	v_mfma_f32_16x16x32_bf16 v[130:133], v[134:137], v[216:219], v[130:133]
	v_mfma_f32_16x16x32_bf16 v[126:129], v[154:157], v[216:219], v[126:129]
	v_mfma_f32_16x16x32_bf16 v[122:125], v[134:137], v[224:227], v[122:125]
	v_mfma_f32_16x16x32_bf16 v[118:121], v[154:157], v[224:227], v[118:121]
	v_mfma_f32_16x16x32_bf16 v[114:117], v[134:137], v[232:235], v[114:117]
	v_mfma_f32_16x16x32_bf16 v[110:113], v[154:157], v[232:235], v[110:113]
	v_mfma_f32_16x16x32_bf16 v[106:109], v[134:137], v[240:243], v[106:109]
	v_mfma_f32_16x16x32_bf16 v[102:105], v[154:157], v[240:243], v[102:105]
	v_mfma_f32_16x16x32_bf16 v[130:133], v[138:141], v[220:223], v[130:133]
	v_mfma_f32_16x16x32_bf16 v[126:129], v[158:161], v[220:223], v[126:129]
	v_mfma_f32_16x16x32_bf16 v[122:125], v[138:141], v[228:231], v[122:125]
	v_mfma_f32_16x16x32_bf16 v[118:121], v[158:161], v[228:231], v[118:121]
	v_mfma_f32_16x16x32_bf16 v[114:117], v[138:141], v[236:239], v[114:117]
	v_mfma_f32_16x16x32_bf16 v[110:113], v[158:161], v[236:239], v[110:113]
	v_mfma_f32_16x16x32_bf16 v[106:109], v[138:141], v[244:247], v[106:109]
	v_mfma_f32_16x16x32_bf16 v[102:105], v[158:161], v[244:247], v[102:105]
	v_mfma_f32_16x16x32_bf16 v[98:101], v[178:181], v[216:219], v[98:101]
	v_mfma_f32_16x16x32_bf16 v[94:97], v[208:211], v[216:219], v[94:97]
	v_mfma_f32_16x16x32_bf16 v[90:93], v[178:181], v[224:227], v[90:93]
	v_mfma_f32_16x16x32_bf16 v[86:89], v[208:211], v[224:227], v[86:89]
	v_mfma_f32_16x16x32_bf16 v[82:85], v[178:181], v[232:235], v[82:85]
	v_mfma_f32_16x16x32_bf16 v[78:81], v[208:211], v[232:235], v[78:81]
	v_mfma_f32_16x16x32_bf16 v[74:77], v[178:181], v[240:243], v[74:77]
	v_mfma_f32_16x16x32_bf16 v[70:73], v[208:211], v[240:243], v[70:73]
	v_mfma_f32_16x16x32_bf16 v[98:101], v[204:207], v[220:223], v[98:101]
	v_mfma_f32_16x16x32_bf16 v[94:97], v[212:215], v[220:223], v[94:97]
	v_mfma_f32_16x16x32_bf16 v[90:93], v[204:207], v[228:231], v[90:93]
	v_mfma_f32_16x16x32_bf16 v[86:89], v[212:215], v[228:231], v[86:89]
	v_mfma_f32_16x16x32_bf16 v[82:85], v[204:207], v[236:239], v[82:85]
	v_mfma_f32_16x16x32_bf16 v[78:81], v[212:215], v[236:239], v[78:81]
	v_mfma_f32_16x16x32_bf16 v[74:77], v[204:207], v[244:247], v[74:77]
	v_mfma_f32_16x16x32_bf16 v[70:73], v[212:215], v[244:247], v[70:73]
	s_setprio 3
	s_barrier
	s_add_i32 s29, s31, s54
	s_mov_b32 m0, s29
	ds_read_b128 v[216:219], v177 offset:16384
	ds_read_b128 v[220:223], v177 offset:17408
	ds_read_b128 v[224:227], v177 offset:18432
	ds_read_b128 v[228:231], v177 offset:19456
	ds_read_b128 v[232:235], v177 offset:20480
	ds_read_b128 v[236:239], v177 offset:21504
	ds_read_b128 v[240:243], v177 offset:22528
	ds_read_b128 v[244:247], v177 offset:23552
	global_load_lds_dwordx4 v144, s[42:43]
	s_add_i32 m0, s29, 0x2000
	s_add_u32 s64, s42, 0x40000
	s_addc_u32 s65, s43, 0
	s_add_i32 s27, s27, s54
	global_load_lds_dwordx4 v148, s[42:43]
	s_mov_b32 m0, s27
	s_nop 0
	global_load_lds_dwordx4 v144, s[64:65]
	s_add_i32 m0, s27, 0x2000
	s_nop 0
	global_load_lds_dwordx4 v148, s[64:65]
	s_mov_b32 m0, s55
	s_nop 0
	global_load_lds_dwordx4 v142, s[44:45]
	s_mov_b32 m0, s56
	s_nop 0
	global_load_lds_dwordx4 v146, s[44:45]
	s_nop 0
	s_waitcnt vmcnt(8) lgkmcnt(0)
	s_barrier
; #define PG8_STAGE(bufoff, gbase, voff) do { _Pragma("unroll") for (int _i = 0; _i < 2; ++_i) \
;         __builtin_amdgcn_global_load_lds((const unsigned*)((const char*)(gbase) + (voff)[_i]), (PG8_LAS unsigned*)(lds + (bufoff) + ldsw + _i * 8192), 16, 0, 0); } while (0)
; #define PG8_LDA(dst, b, h) do { _Pragma("unroll") for (int m = 0; m < 4; ++m) _Pragma("unroll") for (int k = 0; k < 2; ++k) dst[m][k] = *(const PG8_LAS bf16x8*)(lds + PG8_SA(b, h) + aoff + m * 2048 + k * 1024); } while (0)
; #define PG8_LDB(dst, b, h) do { _Pragma("unroll") for (int n = 0; n < 2; ++n) _Pragma("unroll") for (int k = 0; k < 2; ++k) dst[n][k] = *(const PG8_LAS bf16x8*)(lds + PG8_SB(b, h) + boff + n * 2048 + k * 1024); } while (0)
; #define PG8_MMA(ai, bj, At, Bt) do { __builtin_amdgcn_s_setprio(1); _Pragma("unroll") for (int m = 0; m < 4; ++m) _Pragma("unroll") for (int n = 0; n < 2; ++n) _Pragma("unroll") for (int k = 0; k < 2; ++k) \
;         acc[ai][bj][m][n] = __builtin_amdgcn_mfma_f32_16x16x32_bf16(Bt[n][k], At[m][k], acc[ai][bj][m][n], 0, 0, 0); __builtin_amdgcn_s_setprio(0); } while (0)
; #define PG8_WAIT_V(n) asm volatile("s_waitcnt vmcnt(" #n ")" ::: "memory")
; #define PG8_WAIT_L(n) asm volatile("s_waitcnt lgkmcnt(" #n ")" ::: "memory")
; #define PG8_BAR __builtin_amdgcn_s_barrier()
; #define PG8_SCHED __builtin_amdgcn_sched_barrier(0)
; template <class Epi, class Sched, bool ALIGN_EPI = false, bool SP2 = false>
; __device__ __forceinline__ void gemm_phase(PG8_LAS unsigned char* lds, const Gemm g, const Sched& S, const Epi& E) {
;     ...
;             PG8_LDA(At, 0, 1); PG8_STAGE(PG8_SB(0, 0), b2, voffB); PG8_STAGE(PG8_SB(0, 1), b2 + hstep, voffB); PG8_STAGE(PG8_SA(0, 0), a2, voffA);
;             PG8_WAIT_V(8); PG8_WAIT_L(0); PG8_BAR; PG8_MMA(1, 0, At, B0); PG8_MMA(1, 1, At, B1); PG8_BAR; PG8_SCHED;
;             PG8_LDB(B0, 1, 0); PG8_LDB(B1, 1, 1); PG8_SCHED; PG8_LDA(At, 1, 0); PG8_STAGE(PG8_SA(0, 1), a2 + hstep, voffA);
;             PG8_WAIT_V(8); PG8_WAIT_L(0); PG8_BAR; PG8_MMA(0, 0, At, B0); PG8_MMA(0, 1, At, B1); PG8_BAR; PG8_SCHED;
	s_setprio 0
	s_waitcnt lgkmcnt(0)
	v_mfma_f32_16x16x32_bf16 v[66:69], v[134:137], v[216:219], v[66:69]
	v_mfma_f32_16x16x32_bf16 v[62:65], v[154:157], v[216:219], v[62:65]
	v_mfma_f32_16x16x32_bf16 v[58:61], v[134:137], v[224:227], v[58:61]
	v_mfma_f32_16x16x32_bf16 v[54:57], v[154:157], v[224:227], v[54:57]
	v_mfma_f32_16x16x32_bf16 v[50:53], v[134:137], v[232:235], v[50:53]
	v_mfma_f32_16x16x32_bf16 v[46:49], v[154:157], v[232:235], v[46:49]
	v_mfma_f32_16x16x32_bf16 v[42:45], v[134:137], v[240:243], v[42:45]
	v_mfma_f32_16x16x32_bf16 v[38:41], v[154:157], v[240:243], v[38:41]
	v_mfma_f32_16x16x32_bf16 v[66:69], v[138:141], v[220:223], v[66:69]
	v_mfma_f32_16x16x32_bf16 v[62:65], v[158:161], v[220:223], v[62:65]
	v_mfma_f32_16x16x32_bf16 v[58:61], v[138:141], v[228:231], v[58:61]
	v_mfma_f32_16x16x32_bf16 v[54:57], v[158:161], v[228:231], v[54:57]
	v_mfma_f32_16x16x32_bf16 v[50:53], v[138:141], v[236:239], v[50:53]
	v_mfma_f32_16x16x32_bf16 v[46:49], v[158:161], v[236:239], v[46:49]
	v_mfma_f32_16x16x32_bf16 v[42:45], v[138:141], v[244:247], v[42:45]
	v_mfma_f32_16x16x32_bf16 v[38:41], v[158:161], v[244:247], v[38:41]
	v_mfma_f32_16x16x32_bf16 v[34:37], v[178:181], v[216:219], v[34:37]
	v_mfma_f32_16x16x32_bf16 v[30:33], v[208:211], v[216:219], v[30:33]
	v_mfma_f32_16x16x32_bf16 v[26:29], v[178:181], v[224:227], v[26:29]
	v_mfma_f32_16x16x32_bf16 v[22:25], v[208:211], v[224:227], v[22:25]
	v_mfma_f32_16x16x32_bf16 v[18:21], v[178:181], v[232:235], v[18:21]
	v_mfma_f32_16x16x32_bf16 v[14:17], v[208:211], v[232:235], v[14:17]
	v_mfma_f32_16x16x32_bf16 v[10:13], v[178:181], v[240:243], v[10:13]
	v_mfma_f32_16x16x32_bf16 v[4:7], v[208:211], v[240:243], v[6:9]
	v_mfma_f32_16x16x32_bf16 v[34:37], v[204:207], v[220:223], v[34:37]
	v_mfma_f32_16x16x32_bf16 v[30:33], v[212:215], v[220:223], v[30:33]
	v_mfma_f32_16x16x32_bf16 v[26:29], v[204:207], v[228:231], v[26:29]
	v_mfma_f32_16x16x32_bf16 v[22:25], v[212:215], v[228:231], v[22:25]
	v_mfma_f32_16x16x32_bf16 v[18:21], v[204:207], v[236:239], v[18:21]
	v_mfma_f32_16x16x32_bf16 v[14:17], v[212:215], v[236:239], v[14:17]
	v_mfma_f32_16x16x32_bf16 v[10:13], v[204:207], v[244:247], v[10:13]
	v_mfma_f32_16x16x32_bf16 v[4:7], v[212:215], v[244:247], v[4:7]
	s_setprio 3
	s_barrier
	s_add_i32 s27, 0, 0x18000
	s_add_i32 s29, 0, 0x1c000
	ds_read_b128 v[134:137], v175 offset:32768
	ds_read_b128 v[138:141], v175 offset:33792
	ds_read_b128 v[154:157], v175 offset:34816
	ds_read_b128 v[158:161], v175 offset:35840
	ds_read_b128 v[178:181], v175 offset:49152
	ds_read_b128 v[204:207], v175 offset:50176
	ds_read_b128 v[208:211], v175 offset:51200
	ds_read_b128 v[212:215], v175 offset:52224
	s_add_u32 s100, s44, 0x80
	s_addc_u32 s101, s45, 0
	s_add_u32 s44, s44, 0x40000
	s_addc_u32 s45, s45, 0
	s_mov_b32 m0, s57
	ds_read_b128 v[216:219], v177 offset:32768
	ds_read_b128 v[220:223], v177 offset:33792
	ds_read_b128 v[224:227], v177 offset:34816
	ds_read_b128 v[228:231], v177 offset:35840
	ds_read_b128 v[232:235], v177 offset:36864
	ds_read_b128 v[236:239], v177 offset:37888
	ds_read_b128 v[240:243], v177 offset:38912
	ds_read_b128 v[244:247], v177 offset:39936
	global_load_lds_dwordx4 v142, s[44:45]
	s_mov_b32 m0, s58
	s_nop 0
	global_load_lds_dwordx4 v146, s[44:45]
	s_nop 0
	s_waitcnt vmcnt(8) lgkmcnt(0)
	s_barrier
	s_setprio 0
	s_waitcnt lgkmcnt(0)
	v_mfma_f32_16x16x32_bf16 v[130:133], v[134:137], v[216:219], v[130:133]
	v_mfma_f32_16x16x32_bf16 v[126:129], v[154:157], v[216:219], v[126:129]
	v_mfma_f32_16x16x32_bf16 v[122:125], v[134:137], v[224:227], v[122:125]
	v_mfma_f32_16x16x32_bf16 v[118:121], v[154:157], v[224:227], v[118:121]
	v_mfma_f32_16x16x32_bf16 v[114:117], v[134:137], v[232:235], v[114:117]
	v_mfma_f32_16x16x32_bf16 v[110:113], v[154:157], v[232:235], v[110:113]
	v_mfma_f32_16x16x32_bf16 v[106:109], v[134:137], v[240:243], v[106:109]
	v_mfma_f32_16x16x32_bf16 v[102:105], v[154:157], v[240:243], v[102:105]
	v_mfma_f32_16x16x32_bf16 v[130:133], v[138:141], v[220:223], v[130:133]
	v_mfma_f32_16x16x32_bf16 v[126:129], v[158:161], v[220:223], v[126:129]
	v_mfma_f32_16x16x32_bf16 v[122:125], v[138:141], v[228:231], v[122:125]
	v_mfma_f32_16x16x32_bf16 v[118:121], v[158:161], v[228:231], v[118:121]
	v_mfma_f32_16x16x32_bf16 v[114:117], v[138:141], v[236:239], v[114:117]
	v_mfma_f32_16x16x32_bf16 v[110:113], v[158:161], v[236:239], v[110:113]
	v_mfma_f32_16x16x32_bf16 v[106:109], v[138:141], v[244:247], v[106:109]
	v_mfma_f32_16x16x32_bf16 v[102:105], v[158:161], v[244:247], v[102:105]
	v_mfma_f32_16x16x32_bf16 v[98:101], v[178:181], v[216:219], v[98:101]
	v_mfma_f32_16x16x32_bf16 v[94:97], v[208:211], v[216:219], v[94:97]
	v_mfma_f32_16x16x32_bf16 v[90:93], v[178:181], v[224:227], v[90:93]
	v_mfma_f32_16x16x32_bf16 v[86:89], v[208:211], v[224:227], v[86:89]
	v_mfma_f32_16x16x32_bf16 v[82:85], v[178:181], v[232:235], v[82:85]
	v_mfma_f32_16x16x32_bf16 v[78:81], v[208:211], v[232:235], v[78:81]
	v_mfma_f32_16x16x32_bf16 v[74:77], v[178:181], v[240:243], v[74:77]
	v_mfma_f32_16x16x32_bf16 v[70:73], v[208:211], v[240:243], v[70:73]
	v_mfma_f32_16x16x32_bf16 v[98:101], v[204:207], v[220:223], v[98:101]
	v_mfma_f32_16x16x32_bf16 v[94:97], v[212:215], v[220:223], v[94:97]
	v_mfma_f32_16x16x32_bf16 v[90:93], v[204:207], v[228:231], v[90:93]
	v_mfma_f32_16x16x32_bf16 v[86:89], v[212:215], v[228:231], v[86:89]
	v_mfma_f32_16x16x32_bf16 v[82:85], v[204:207], v[236:239], v[82:85]
	v_mfma_f32_16x16x32_bf16 v[78:81], v[212:215], v[236:239], v[78:81]
	v_mfma_f32_16x16x32_bf16 v[74:77], v[204:207], v[244:247], v[74:77]
	v_mfma_f32_16x16x32_bf16 v[70:73], v[212:215], v[244:247], v[70:73]
	s_setprio 3
	s_barrier
; #define PG8_STAGE(bufoff, gbase, voff) do { _Pragma("unroll") for (int _i = 0; _i < 2; ++_i) \
;         __builtin_amdgcn_global_load_lds((const unsigned*)((const char*)(gbase) + (voff)[_i]), (PG8_LAS unsigned*)(lds + (bufoff) + ldsw + _i * 8192), 16, 0, 0); } while (0)
; #define PG8_LDA(dst, b, h) do { _Pragma("unroll") for (int m = 0; m < 4; ++m) _Pragma("unroll") for (int k = 0; k < 2; ++k) dst[m][k] = *(const PG8_LAS bf16x8*)(lds + PG8_SA(b, h) + aoff + m * 2048 + k * 1024); } while (0)
; #define PG8_MMA(ai, bj, At, Bt) do { __builtin_amdgcn_s_setprio(1); _Pragma("unroll") for (int m = 0; m < 4; ++m) _Pragma("unroll") for (int n = 0; n < 2; ++n) _Pragma("unroll") for (int k = 0; k < 2; ++k) \
;         acc[ai][bj][m][n] = __builtin_amdgcn_mfma_f32_16x16x32_bf16(Bt[n][k], At[m][k], acc[ai][bj][m][n], 0, 0, 0); __builtin_amdgcn_s_setprio(0); } while (0)
; #define PG8_WAIT_V(n) asm volatile("s_waitcnt vmcnt(" #n ")" ::: "memory")
; #define PG8_WAIT_L(n) asm volatile("s_waitcnt lgkmcnt(" #n ")" ::: "memory")
; #define PG8_BAR __builtin_amdgcn_s_barrier()
; #define PG8_SCHED __builtin_amdgcn_sched_barrier(0)
; template <class Epi, class Sched, bool ALIGN_EPI = false, bool SP2 = false>
; __device__ __forceinline__ void gemm_phase(PG8_LAS unsigned char* lds, const Gemm g, const Sched& S, const Epi& E) {
;     ...
;             PG8_LDA(At, 1, 1); PG8_STAGE(PG8_SB(1, 0), b3, voffB); PG8_STAGE(PG8_SB(1, 1), b3 + hstep, voffB); PG8_STAGE(PG8_SA(1, 0), a3, voffA);
;             PG8_WAIT_V(8); PG8_WAIT_L(0); PG8_BAR; PG8_MMA(1, 0, At, B0); PG8_MMA(1, 1, At, B1); PG8_BAR; PG8_SCHED;
	s_add_i32 s27, s27, s54
	s_add_i32 m0, s27, 0xffffff80
	ds_read_b128 v[216:219], v177 offset:49152
	ds_read_b128 v[220:223], v177 offset:50176
	ds_read_b128 v[224:227], v177 offset:51200
	ds_read_b128 v[228:231], v177 offset:52224
	ds_read_b128 v[232:235], v177 offset:53248
	ds_read_b128 v[236:239], v177 offset:54272
	ds_read_b128 v[240:243], v177 offset:55296
	ds_read_b128 v[244:247], v177 offset:56320
	global_load_lds_dwordx4 v144, s[42:43] offset:128
	s_add_i32 m0, s27, 0x1f80
	s_add_i32 s27, s29, s54
	global_load_lds_dwordx4 v148, s[42:43] offset:128
	s_add_u32 s42, s42, 0x40080
	s_addc_u32 s43, s43, 0
	s_mov_b32 m0, s27
	s_nop 0
	global_load_lds_dwordx4 v144, s[42:43]
	s_add_i32 m0, s27, 0x2000
	s_nop 0
	global_load_lds_dwordx4 v148, s[42:43]
	s_mov_b32 m0, s61
	s_nop 0
	global_load_lds_dwordx4 v142, s[100:101]
	s_mov_b32 m0, s62
	s_nop 0
	global_load_lds_dwordx4 v146, s[100:101]
	s_waitcnt vmcnt(8) lgkmcnt(0)
	s_barrier
	s_setprio 0
	s_waitcnt lgkmcnt(0)
	v_mfma_f32_16x16x32_bf16 v[66:69], v[134:137], v[216:219], v[66:69]
	v_mfma_f32_16x16x32_bf16 v[62:65], v[154:157], v[216:219], v[62:65]
	v_mfma_f32_16x16x32_bf16 v[58:61], v[134:137], v[224:227], v[58:61]
	v_mfma_f32_16x16x32_bf16 v[54:57], v[154:157], v[224:227], v[54:57]
	v_mfma_f32_16x16x32_bf16 v[50:53], v[134:137], v[232:235], v[50:53]
	v_mfma_f32_16x16x32_bf16 v[46:49], v[154:157], v[232:235], v[46:49]
	v_mfma_f32_16x16x32_bf16 v[42:45], v[134:137], v[240:243], v[42:45]
	v_mfma_f32_16x16x32_bf16 v[38:41], v[154:157], v[240:243], v[38:41]
	v_mfma_f32_16x16x32_bf16 v[66:69], v[138:141], v[220:223], v[66:69]
	v_mfma_f32_16x16x32_bf16 v[62:65], v[158:161], v[220:223], v[62:65]
	v_mfma_f32_16x16x32_bf16 v[58:61], v[138:141], v[228:231], v[58:61]
	v_mfma_f32_16x16x32_bf16 v[54:57], v[158:161], v[228:231], v[54:57]
	v_mfma_f32_16x16x32_bf16 v[50:53], v[138:141], v[236:239], v[50:53]
	v_mfma_f32_16x16x32_bf16 v[46:49], v[158:161], v[236:239], v[46:49]
	v_mfma_f32_16x16x32_bf16 v[42:45], v[138:141], v[244:247], v[42:45]
	v_mfma_f32_16x16x32_bf16 v[38:41], v[158:161], v[244:247], v[38:41]
	v_mfma_f32_16x16x32_bf16 v[34:37], v[178:181], v[216:219], v[34:37]
	v_mfma_f32_16x16x32_bf16 v[30:33], v[208:211], v[216:219], v[30:33]
	v_mfma_f32_16x16x32_bf16 v[26:29], v[178:181], v[224:227], v[26:29]
	v_mfma_f32_16x16x32_bf16 v[22:25], v[208:211], v[224:227], v[22:25]
	v_mfma_f32_16x16x32_bf16 v[18:21], v[178:181], v[232:235], v[18:21]
	v_mfma_f32_16x16x32_bf16 v[14:17], v[208:211], v[232:235], v[14:17]
	v_mfma_f32_16x16x32_bf16 v[8:11], v[178:181], v[240:243], v[10:13]
	v_mfma_f32_16x16x32_bf16 v[4:7], v[208:211], v[240:243], v[4:7]
	v_mfma_f32_16x16x32_bf16 v[34:37], v[204:207], v[220:223], v[34:37]
	v_mfma_f32_16x16x32_bf16 v[30:33], v[212:215], v[220:223], v[30:33]
	v_mfma_f32_16x16x32_bf16 v[26:29], v[204:207], v[228:231], v[26:29]
	v_mfma_f32_16x16x32_bf16 v[22:25], v[212:215], v[228:231], v[22:25]
	v_mfma_f32_16x16x32_bf16 v[18:21], v[204:207], v[236:239], v[18:21]
	v_mfma_f32_16x16x32_bf16 v[14:17], v[212:215], v[236:239], v[14:17]
	v_mfma_f32_16x16x32_bf16 v[10:13], v[204:207], v[244:247], v[8:11]
	v_mfma_f32_16x16x32_bf16 v[6:9], v[212:215], v[244:247], v[4:7]
	s_setprio 3
	s_barrier
	s_add_i32 s26, s26, 2
	s_add_u32 s40, s40, 0x100
	s_addc_u32 s41, s41, 0
	s_add_u32 s11, s11, 0x100
	s_addc_u32 s13, s13, 0
	s_cmp_gt_u32 s26, 13
	s_cbranch_scc0 .LBB0_2096
	s_and_b64 vcc, exec, s[8:9]
	s_cbranch_vccz .LBB0_2099
	s_barrier

; #define PG8_STAGE(bufoff, gbase, voff) do { _Pragma("unroll") for (int _i = 0; _i < 2; ++_i) \
;         __builtin_amdgcn_global_load_lds((const unsigned*)((const char*)(gbase) + (voff)[_i]), (PG8_LAS unsigned*)(lds + (bufoff) + ldsw + _i * 8192), 16, 0, 0); } while (0)
; #define PG8_LDA(dst, b, h) do { _Pragma("unroll") for (int m = 0; m < 4; ++m) _Pragma("unroll") for (int k = 0; k < 2; ++k) dst[m][k] = *(const PG8_LAS bf16x8*)(lds + PG8_SA(b, h) + aoff + m * 2048 + k * 1024); } while (0)
; #define PG8_LDB(dst, b, h) do { _Pragma("unroll") for (int n = 0; n < 2; ++n) _Pragma("unroll") for (int k = 0; k < 2; ++k) dst[n][k] = *(const PG8_LAS bf16x8*)(lds + PG8_SB(b, h) + boff + n * 2048 + k * 1024); } while (0)
; #define PG8_MMA(ai, bj, At, Bt) do { __builtin_amdgcn_s_setprio(1); _Pragma("unroll") for (int m = 0; m < 4; ++m) _Pragma("unroll") for (int n = 0; n < 2; ++n) _Pragma("unroll") for (int k = 0; k < 2; ++k) \
;         acc[ai][bj][m][n] = __builtin_amdgcn_mfma_f32_16x16x32_bf16(Bt[n][k], At[m][k], acc[ai][bj][m][n], 0, 0, 0); __builtin_amdgcn_s_setprio(0); } while (0)
; #define PG8_WAIT_V(n) asm volatile("s_waitcnt vmcnt(" #n ")" ::: "memory")
; template <class Epi, class Sched, bool ALIGN_EPI = false, bool SP2 = false>
; __device__ __forceinline__ void gemm_phase(PG8_LAS unsigned char* lds, const Gemm g, const Sched& S, const Epi& E) {
;     ...
;         for (int t = 0; t < nt; t += 2) {
;             const bool last = (t == nt - 2);
;             const char* a1 = cA + (size_t)(t + 1) * kstep;
;             const char* a2 = last ? nA : cA + (size_t)(t + 2) * kstep; const char* b2 = last ? nB : cB + (size_t)(t + 2) * kstep;
;             const char* a3 = a2 + kstep; const char* b3 = b2 + kstep;
;             if (last && has_next) S.a_ready(nxt);
;             if constexpr (SP2) {
;             PG8_LDB(B0, 0, 0); PG8_LDB(B1, 0, 1); PG8_SCHED; PG8_LDA(At, 0, 0); PG8_STAGE(PG8_SA(1, 1), a1 + hstep, voffA);
;             PG8_WAIT_V(8); PG8_WAIT_L(0); PG8_BAR; PG8_MMA(0, 0, At, B0); PG8_MMA(0, 1, At, B1); PG8_BAR; PG8_SCHED;
;     ...
;         if (zero_acc) {
; #pragma unroll
;         for (int a = 0; a < 2; ++a)
; #pragma unroll
;             for (int b = 0; b < 2; ++b)
; #pragma unroll
;                 for (int m = 0; m < 4; ++m)
; #pragma unroll
;                     for (int n = 0; n < 2; ++n) acc[a][b][m][n] = (f32x4){0.f, 0.f, 0.f, 0.f};
.LBB0_2184:
	s_add_u32 s2, s42, 0x100
	v_mov_b32_e32 v4, 0
	s_addc_u32 s29, s43, 0
	s_mov_b32 s31, -2
	s_waitcnt lgkmcnt(0)
	v_mov_b32_e32 v5, v4
	v_mov_b32_e32 v6, v4
	v_mov_b32_e32 v7, v4
	v_mov_b32_e32 v8, v4
	v_mov_b32_e32 v9, v4
	v_mov_b32_e32 v10, v4
	v_mov_b32_e32 v11, v4
	v_mov_b32_e32 v20, v4
	v_mov_b32_e32 v21, v4
	v_mov_b32_e32 v22, v4
	v_mov_b32_e32 v23, v4
	v_mov_b32_e32 v24, v4
	v_mov_b32_e32 v25, v4
	v_mov_b32_e32 v26, v4
	v_mov_b32_e32 v27, v4
	v_mov_b32_e32 v36, v4
	v_mov_b32_e32 v37, v4
	v_mov_b32_e32 v38, v4
	v_mov_b32_e32 v39, v4
	v_mov_b32_e32 v40, v4
	v_mov_b32_e32 v41, v4
	v_mov_b32_e32 v42, v4
	v_mov_b32_e32 v43, v4
	v_mov_b32_e32 v52, v4
	v_mov_b32_e32 v53, v4
	v_mov_b32_e32 v54, v4
	v_mov_b32_e32 v55, v4
	v_mov_b32_e32 v56, v4
	v_mov_b32_e32 v57, v4
	v_mov_b32_e32 v58, v4
	v_mov_b32_e32 v59, v4
	v_mov_b32_e32 v12, v4
	v_mov_b32_e32 v13, v4
	v_mov_b32_e32 v14, v4
	v_mov_b32_e32 v15, v4
	v_mov_b32_e32 v16, v4
	v_mov_b32_e32 v17, v4
	v_mov_b32_e32 v18, v4
	v_mov_b32_e32 v19, v4
	v_mov_b32_e32 v28, v4
	v_mov_b32_e32 v29, v4
	v_mov_b32_e32 v30, v4
	v_mov_b32_e32 v31, v4
	v_mov_b32_e32 v32, v4
	v_mov_b32_e32 v33, v4
	v_mov_b32_e32 v34, v4
	v_mov_b32_e32 v35, v4
	v_mov_b32_e32 v44, v4
	v_mov_b32_e32 v45, v4
	v_mov_b32_e32 v46, v4
	v_mov_b32_e32 v47, v4
	v_mov_b32_e32 v48, v4
	v_mov_b32_e32 v49, v4
	v_mov_b32_e32 v50, v4
	v_mov_b32_e32 v51, v4
	v_mov_b32_e32 v60, v4
	v_mov_b32_e32 v61, v4
	v_mov_b32_e32 v62, v4
	v_mov_b32_e32 v63, v4
	v_mov_b32_e32 v64, v4
	v_mov_b32_e32 v65, v4
	v_mov_b32_e32 v66, v4
	v_mov_b32_e32 v67, v4
	v_mov_b32_e32 v68, v4
	v_mov_b32_e32 v69, v4
	v_mov_b32_e32 v70, v4
	v_mov_b32_e32 v71, v4
	v_mov_b32_e32 v72, v4
	v_mov_b32_e32 v73, v4
	v_mov_b32_e32 v74, v4
	v_mov_b32_e32 v75, v4
	v_mov_b32_e32 v84, v4
	v_mov_b32_e32 v85, v4
	v_mov_b32_e32 v86, v4
	v_mov_b32_e32 v87, v4
	v_mov_b32_e32 v88, v4
	v_mov_b32_e32 v89, v4
	v_mov_b32_e32 v90, v4
	v_mov_b32_e32 v91, v4
	v_mov_b32_e32 v100, v4
	v_mov_b32_e32 v101, v4
	v_mov_b32_e32 v102, v4
	v_mov_b32_e32 v103, v4
	v_mov_b32_e32 v104, v4
	v_mov_b32_e32 v105, v4
	v_mov_b32_e32 v106, v4
	v_mov_b32_e32 v107, v4
	v_mov_b32_e32 v116, v4
	v_mov_b32_e32 v117, v4
	v_mov_b32_e32 v118, v4
	v_mov_b32_e32 v119, v4
	v_mov_b32_e32 v120, v4
	v_mov_b32_e32 v121, v4
	v_mov_b32_e32 v122, v4
	v_mov_b32_e32 v123, v4
	v_mov_b32_e32 v76, v4
	v_mov_b32_e32 v77, v4
	v_mov_b32_e32 v78, v4
	v_mov_b32_e32 v79, v4
	v_mov_b32_e32 v80, v4
	v_mov_b32_e32 v81, v4
	v_mov_b32_e32 v82, v4
	v_mov_b32_e32 v83, v4
	v_mov_b32_e32 v92, v4
	v_mov_b32_e32 v93, v4
	v_mov_b32_e32 v94, v4
	v_mov_b32_e32 v95, v4
	v_mov_b32_e32 v96, v4
	v_mov_b32_e32 v97, v4
	v_mov_b32_e32 v98, v4
	v_mov_b32_e32 v99, v4
	v_mov_b32_e32 v108, v4
	v_mov_b32_e32 v109, v4
	v_mov_b32_e32 v110, v4
	v_mov_b32_e32 v111, v4
	v_mov_b32_e32 v112, v4
	v_mov_b32_e32 v113, v4
	v_mov_b32_e32 v114, v4
	v_mov_b32_e32 v115, v4
	v_mov_b32_e32 v124, v4
	v_mov_b32_e32 v125, v4
	v_mov_b32_e32 v126, v4
	v_mov_b32_e32 v127, v4
	v_mov_b32_e32 v128, v4
	v_mov_b32_e32 v129, v4
	v_mov_b32_e32 v130, v4
	v_mov_b32_e32 v131, v4
	v_add_u32_e32 v243, 0x10000, v173
	.p2align 6
	s_nop 0
.LBB0_2185:
	s_add_u32 s42, s40, 0x100
	s_addc_u32 s43, s41, 0
	s_add_i32 s37, 0, 0x10000
	s_cmp_eq_u32 s31, 28
	s_cselect_b32 s47, s5, s43
	s_cselect_b32 s46, s4, s42
	s_cselect_b32 s45, s35, s29
	s_cselect_b32 s44, s34, s2
	s_add_i32 s39, 0, 0x14000
	ds_read_b128 v[142:145], v243
	ds_read_b128 v[146:149], v243 offset:1024
	ds_read_b128 v[150:153], v243 offset:2048
	ds_read_b128 v[154:157], v243 offset:3072
	ds_read_b128 v[158:161], v243 offset:16384
	ds_read_b128 v[174:177], v243 offset:17408
	ds_read_b128 v[180:183], v243 offset:18432
	ds_read_b128 v[204:207], v243 offset:19456
	v_lshl_add_u64 v[162:163], s[40:41], 0, v[138:139]
	s_add_i32 m0, s55, 0xc000
	ds_read_b128 v[208:211], v179
	ds_read_b128 v[212:215], v179 offset:1024
	ds_read_b128 v[216:219], v179 offset:2048
	ds_read_b128 v[220:223], v179 offset:3072
	ds_read_b128 v[224:227], v179 offset:4096
	ds_read_b128 v[228:231], v179 offset:5120
	ds_read_b128 v[232:235], v179 offset:6144
	ds_read_b128 v[236:239], v179 offset:7168
	global_load_lds_dwordx4 v[162:163], off
	v_lshl_add_u64 v[162:163], s[40:41], 0, v[140:141]
	s_add_i32 m0, s55, 0xe000
	s_nop 0
	global_load_lds_dwordx4 v[162:163], off
	s_nop 0
	s_waitcnt vmcnt(8) lgkmcnt(0)
	s_barrier
	s_setprio 0
	s_waitcnt lgkmcnt(0)
	v_mfma_f32_16x16x32_bf16 v[128:131], v[142:145], v[208:211], v[128:131]
	v_mfma_f32_16x16x32_bf16 v[124:127], v[150:153], v[208:211], v[124:127]
	v_mfma_f32_16x16x32_bf16 v[112:115], v[142:145], v[216:219], v[112:115]
	v_mfma_f32_16x16x32_bf16 v[108:111], v[150:153], v[216:219], v[108:111]
	v_mfma_f32_16x16x32_bf16 v[96:99], v[142:145], v[224:227], v[96:99]
	v_mfma_f32_16x16x32_bf16 v[92:95], v[150:153], v[224:227], v[92:95]
	v_mfma_f32_16x16x32_bf16 v[80:83], v[142:145], v[232:235], v[80:83]
	v_mfma_f32_16x16x32_bf16 v[76:79], v[150:153], v[232:235], v[76:79]
	v_mfma_f32_16x16x32_bf16 v[128:131], v[146:149], v[212:215], v[128:131]
	v_mfma_f32_16x16x32_bf16 v[124:127], v[154:157], v[212:215], v[124:127]
	v_mfma_f32_16x16x32_bf16 v[112:115], v[146:149], v[220:223], v[112:115]
	v_mfma_f32_16x16x32_bf16 v[108:111], v[154:157], v[220:223], v[108:111]
	v_mfma_f32_16x16x32_bf16 v[96:99], v[146:149], v[228:231], v[96:99]
	v_mfma_f32_16x16x32_bf16 v[92:95], v[154:157], v[228:231], v[92:95]
	v_mfma_f32_16x16x32_bf16 v[80:83], v[146:149], v[236:239], v[80:83]
	v_mfma_f32_16x16x32_bf16 v[76:79], v[154:157], v[236:239], v[76:79]
	v_mfma_f32_16x16x32_bf16 v[120:123], v[158:161], v[208:211], v[120:123]
	v_mfma_f32_16x16x32_bf16 v[116:119], v[180:183], v[208:211], v[116:119]
	v_mfma_f32_16x16x32_bf16 v[104:107], v[158:161], v[216:219], v[104:107]
	v_mfma_f32_16x16x32_bf16 v[100:103], v[180:183], v[216:219], v[100:103]
	v_mfma_f32_16x16x32_bf16 v[88:91], v[158:161], v[224:227], v[88:91]
	v_mfma_f32_16x16x32_bf16 v[84:87], v[180:183], v[224:227], v[84:87]
	v_mfma_f32_16x16x32_bf16 v[72:75], v[158:161], v[232:235], v[72:75]
	v_mfma_f32_16x16x32_bf16 v[68:71], v[180:183], v[232:235], v[68:71]
	v_mfma_f32_16x16x32_bf16 v[120:123], v[174:177], v[212:215], v[120:123]
	v_mfma_f32_16x16x32_bf16 v[116:119], v[204:207], v[212:215], v[116:119]
	v_mfma_f32_16x16x32_bf16 v[104:107], v[174:177], v[220:223], v[104:107]
	v_mfma_f32_16x16x32_bf16 v[100:103], v[204:207], v[220:223], v[100:103]
	v_mfma_f32_16x16x32_bf16 v[88:91], v[174:177], v[228:231], v[88:91]
	v_mfma_f32_16x16x32_bf16 v[84:87], v[204:207], v[228:231], v[84:87]
	v_mfma_f32_16x16x32_bf16 v[72:75], v[174:177], v[236:239], v[72:75]
	v_mfma_f32_16x16x32_bf16 v[68:71], v[204:207], v[236:239], v[68:71]
	s_setprio 3
	s_barrier
; #define PG8_STAGE(bufoff, gbase, voff) do { _Pragma("unroll") for (int _i = 0; _i < 2; ++_i) \
;         __builtin_amdgcn_global_load_lds((const unsigned*)((const char*)(gbase) + (voff)[_i]), (PG8_LAS unsigned*)(lds + (bufoff) + ldsw + _i * 8192), 16, 0, 0); } while (0)
; #define PG8_LDA(dst, b, h) do { _Pragma("unroll") for (int m = 0; m < 4; ++m) _Pragma("unroll") for (int k = 0; k < 2; ++k) dst[m][k] = *(const PG8_LAS bf16x8*)(lds + PG8_SA(b, h) + aoff + m * 2048 + k * 1024); } while (0)
; #define PG8_LDB(dst, b, h) do { _Pragma("unroll") for (int n = 0; n < 2; ++n) _Pragma("unroll") for (int k = 0; k < 2; ++k) dst[n][k] = *(const PG8_LAS bf16x8*)(lds + PG8_SB(b, h) + boff + n * 2048 + k * 1024); } while (0)
; #define PG8_MMA(ai, bj, At, Bt) do { __builtin_amdgcn_s_setprio(1); _Pragma("unroll") for (int m = 0; m < 4; ++m) _Pragma("unroll") for (int n = 0; n < 2; ++n) _Pragma("unroll") for (int k = 0; k < 2; ++k) \
;         acc[ai][bj][m][n] = __builtin_amdgcn_mfma_f32_16x16x32_bf16(Bt[n][k], At[m][k], acc[ai][bj][m][n], 0, 0, 0); __builtin_amdgcn_s_setprio(0); } while (0)
; #define PG8_WAIT_V(n) asm volatile("s_waitcnt vmcnt(" #n ")" ::: "memory")
; #define PG8_WAIT_L(n) asm volatile("s_waitcnt lgkmcnt(" #n ")" ::: "memory")
; #define PG8_BAR __builtin_amdgcn_s_barrier()
; #define PG8_SCHED __builtin_amdgcn_sched_barrier(0)
; template <class Epi, class Sched, bool ALIGN_EPI = false, bool SP2 = false>
; __device__ __forceinline__ void gemm_phase(PG8_LAS unsigned char* lds, const Gemm g, const Sched& S, const Epi& E) {
;     ...
;             PG8_LDA(At, 0, 1); PG8_STAGE(PG8_SB(0, 0), b2, voffB); PG8_STAGE(PG8_SB(0, 1), b2 + hstep, voffB); PG8_STAGE(PG8_SA(0, 0), a2, voffA);
;             PG8_WAIT_V(8); PG8_WAIT_L(0); PG8_BAR; PG8_MMA(1, 0, At, B0); PG8_MMA(1, 1, At, B1); PG8_BAR; PG8_SCHED;
;             PG8_LDB(B0, 1, 0); PG8_LDB(B1, 1, 1); PG8_SCHED; PG8_LDA(At, 1, 0); PG8_STAGE(PG8_SA(0, 1), a2 + hstep, voffA);
;             PG8_WAIT_V(8); PG8_WAIT_L(0); PG8_BAR; PG8_MMA(0, 0, At, B0); PG8_MMA(0, 1, At, B1); PG8_BAR; PG8_SCHED;
	s_add_i32 s37, s37, s54
	s_mov_b32 m0, s37
	ds_read_b128 v[208:211], v179 offset:16384
	ds_read_b128 v[212:215], v179 offset:17408
	ds_read_b128 v[216:219], v179 offset:18432
	ds_read_b128 v[220:223], v179 offset:19456
	ds_read_b128 v[224:227], v179 offset:20480
	ds_read_b128 v[228:231], v179 offset:21504
	ds_read_b128 v[232:235], v179 offset:22528
	ds_read_b128 v[236:239], v179 offset:23552
	global_load_lds_dwordx4 v2, s[44:45]
	s_add_i32 m0, s37, 0x2000
	s_add_u32 s40, s44, 0x80000
	s_addc_u32 s41, s45, 0
	s_add_i32 s37, s39, s54
	global_load_lds_dwordx4 v132, s[44:45]
	s_mov_b32 m0, s37
	s_nop 0
	global_load_lds_dwordx4 v2, s[40:41]
	s_add_i32 m0, s37, 0x2000
	s_nop 0
	global_load_lds_dwordx4 v132, s[40:41]
	s_mov_b32 m0, s55
	s_nop 0
	global_load_lds_dwordx4 v2, s[46:47]
	s_mov_b32 m0, s56
	s_nop 0
	global_load_lds_dwordx4 v132, s[46:47]
	s_nop 0
	s_waitcnt vmcnt(8) lgkmcnt(0)
	s_barrier
	s_setprio 0
	s_waitcnt lgkmcnt(0)
	v_mfma_f32_16x16x32_bf16 v[64:67], v[142:145], v[208:211], v[64:67]
	v_mfma_f32_16x16x32_bf16 v[60:63], v[150:153], v[208:211], v[60:63]
	v_mfma_f32_16x16x32_bf16 v[48:51], v[142:145], v[216:219], v[48:51]
	v_mfma_f32_16x16x32_bf16 v[44:47], v[150:153], v[216:219], v[44:47]
	v_mfma_f32_16x16x32_bf16 v[32:35], v[142:145], v[224:227], v[32:35]
	v_mfma_f32_16x16x32_bf16 v[28:31], v[150:153], v[224:227], v[28:31]
	v_mfma_f32_16x16x32_bf16 v[16:19], v[142:145], v[232:235], v[16:19]
	v_mfma_f32_16x16x32_bf16 v[12:15], v[150:153], v[232:235], v[12:15]
	v_mfma_f32_16x16x32_bf16 v[64:67], v[146:149], v[212:215], v[64:67]
	v_mfma_f32_16x16x32_bf16 v[60:63], v[154:157], v[212:215], v[60:63]
	v_mfma_f32_16x16x32_bf16 v[48:51], v[146:149], v[220:223], v[48:51]
	v_mfma_f32_16x16x32_bf16 v[44:47], v[154:157], v[220:223], v[44:47]
	v_mfma_f32_16x16x32_bf16 v[32:35], v[146:149], v[228:231], v[32:35]
	v_mfma_f32_16x16x32_bf16 v[28:31], v[154:157], v[228:231], v[28:31]
	v_mfma_f32_16x16x32_bf16 v[16:19], v[146:149], v[236:239], v[16:19]
	v_mfma_f32_16x16x32_bf16 v[12:15], v[154:157], v[236:239], v[12:15]
	v_mfma_f32_16x16x32_bf16 v[56:59], v[158:161], v[208:211], v[56:59]
	v_mfma_f32_16x16x32_bf16 v[52:55], v[180:183], v[208:211], v[52:55]
	v_mfma_f32_16x16x32_bf16 v[40:43], v[158:161], v[216:219], v[40:43]
	v_mfma_f32_16x16x32_bf16 v[36:39], v[180:183], v[216:219], v[36:39]
	v_mfma_f32_16x16x32_bf16 v[24:27], v[158:161], v[224:227], v[24:27]
	v_mfma_f32_16x16x32_bf16 v[20:23], v[180:183], v[224:227], v[20:23]
	v_mfma_f32_16x16x32_bf16 v[8:11], v[158:161], v[232:235], v[8:11]
	v_mfma_f32_16x16x32_bf16 v[4:7], v[180:183], v[232:235], v[4:7]
	v_mfma_f32_16x16x32_bf16 v[56:59], v[174:177], v[212:215], v[56:59]
	v_mfma_f32_16x16x32_bf16 v[52:55], v[204:207], v[212:215], v[52:55]
	v_mfma_f32_16x16x32_bf16 v[40:43], v[174:177], v[220:223], v[40:43]
	v_mfma_f32_16x16x32_bf16 v[36:39], v[204:207], v[220:223], v[36:39]
	v_mfma_f32_16x16x32_bf16 v[24:27], v[174:177], v[228:231], v[24:27]
	v_mfma_f32_16x16x32_bf16 v[20:23], v[204:207], v[228:231], v[20:23]
	v_mfma_f32_16x16x32_bf16 v[8:11], v[174:177], v[236:239], v[8:11]
	v_mfma_f32_16x16x32_bf16 v[4:7], v[204:207], v[236:239], v[4:7]
	s_setprio 3
	s_barrier
	s_add_i32 s37, 0, 0x18000
	s_add_i32 s39, 0, 0x1c000
	ds_read_b128 v[142:145], v243 offset:32768
	ds_read_b128 v[146:149], v243 offset:33792
	ds_read_b128 v[150:153], v243 offset:34816
	ds_read_b128 v[154:157], v243 offset:35840
	ds_read_b128 v[158:161], v243 offset:49152
	ds_read_b128 v[174:177], v243 offset:50176
	ds_read_b128 v[180:183], v243 offset:51200
	ds_read_b128 v[204:207], v243 offset:52224
	s_add_u32 s40, s46, 0x80000
	s_addc_u32 s41, s47, 0
	s_mov_b32 m0, s57
	ds_read_b128 v[208:211], v179 offset:32768
	ds_read_b128 v[212:215], v179 offset:33792
	ds_read_b128 v[216:219], v179 offset:34816
	ds_read_b128 v[220:223], v179 offset:35840
	ds_read_b128 v[224:227], v179 offset:36864
	ds_read_b128 v[228:231], v179 offset:37888
	ds_read_b128 v[232:235], v179 offset:38912
	ds_read_b128 v[236:239], v179 offset:39936
	global_load_lds_dwordx4 v2, s[40:41]
	s_mov_b32 m0, s58
	s_nop 0
	global_load_lds_dwordx4 v132, s[40:41]
	s_waitcnt vmcnt(8) lgkmcnt(0)
	s_barrier
; #define PG8_STAGE(bufoff, gbase, voff) do { _Pragma("unroll") for (int _i = 0; _i < 2; ++_i) \
;         __builtin_amdgcn_global_load_lds((const unsigned*)((const char*)(gbase) + (voff)[_i]), (PG8_LAS unsigned*)(lds + (bufoff) + ldsw + _i * 8192), 16, 0, 0); } while (0)
; #define PG8_LDA(dst, b, h) do { _Pragma("unroll") for (int m = 0; m < 4; ++m) _Pragma("unroll") for (int k = 0; k < 2; ++k) dst[m][k] = *(const PG8_LAS bf16x8*)(lds + PG8_SA(b, h) + aoff + m * 2048 + k * 1024); } while (0)
; #define PG8_MMA(ai, bj, At, Bt) do { __builtin_amdgcn_s_setprio(1); _Pragma("unroll") for (int m = 0; m < 4; ++m) _Pragma("unroll") for (int n = 0; n < 2; ++n) _Pragma("unroll") for (int k = 0; k < 2; ++k) \
;         acc[ai][bj][m][n] = __builtin_amdgcn_mfma_f32_16x16x32_bf16(Bt[n][k], At[m][k], acc[ai][bj][m][n], 0, 0, 0); __builtin_amdgcn_s_setprio(0); } while (0)
; #define PG8_WAIT_V(n) asm volatile("s_waitcnt vmcnt(" #n ")" ::: "memory")
; #define PG8_WAIT_L(n) asm volatile("s_waitcnt lgkmcnt(" #n ")" ::: "memory")
; #define PG8_BAR __builtin_amdgcn_s_barrier()
; #define PG8_SCHED __builtin_amdgcn_sched_barrier(0)
; template <class Epi, class Sched, bool ALIGN_EPI = false, bool SP2 = false>
; __device__ __forceinline__ void gemm_phase(PG8_LAS unsigned char* lds, const Gemm g, const Sched& S, const Epi& E) {
;     ...
;             PG8_WAIT_V(8); PG8_WAIT_L(0); PG8_BAR; PG8_MMA(0, 0, At, B0); PG8_MMA(0, 1, At, B1); PG8_BAR; PG8_SCHED;
;             PG8_LDA(At, 1, 1); PG8_STAGE(PG8_SB(1, 0), b3, voffB); PG8_STAGE(PG8_SB(1, 1), b3 + hstep, voffB); PG8_STAGE(PG8_SA(1, 0), a3, voffA);
;             PG8_WAIT_V(8); PG8_WAIT_L(0); PG8_BAR; PG8_MMA(1, 0, At, B0); PG8_MMA(1, 1, At, B1); PG8_BAR; PG8_SCHED;
	s_setprio 0
	s_waitcnt lgkmcnt(0)
	v_mfma_f32_16x16x32_bf16 v[128:131], v[142:145], v[208:211], v[128:131]
	v_mfma_f32_16x16x32_bf16 v[124:127], v[150:153], v[208:211], v[124:127]
	v_mfma_f32_16x16x32_bf16 v[112:115], v[142:145], v[216:219], v[112:115]
	v_mfma_f32_16x16x32_bf16 v[108:111], v[150:153], v[216:219], v[108:111]
	v_mfma_f32_16x16x32_bf16 v[96:99], v[142:145], v[224:227], v[96:99]
	v_mfma_f32_16x16x32_bf16 v[92:95], v[150:153], v[224:227], v[92:95]
	v_mfma_f32_16x16x32_bf16 v[80:83], v[142:145], v[232:235], v[80:83]
	v_mfma_f32_16x16x32_bf16 v[76:79], v[150:153], v[232:235], v[76:79]
	v_mfma_f32_16x16x32_bf16 v[128:131], v[146:149], v[212:215], v[128:131]
	v_mfma_f32_16x16x32_bf16 v[124:127], v[154:157], v[212:215], v[124:127]
	v_mfma_f32_16x16x32_bf16 v[112:115], v[146:149], v[220:223], v[112:115]
	v_mfma_f32_16x16x32_bf16 v[108:111], v[154:157], v[220:223], v[108:111]
	v_mfma_f32_16x16x32_bf16 v[96:99], v[146:149], v[228:231], v[96:99]
	v_mfma_f32_16x16x32_bf16 v[92:95], v[154:157], v[228:231], v[92:95]
	v_mfma_f32_16x16x32_bf16 v[80:83], v[146:149], v[236:239], v[80:83]
	v_mfma_f32_16x16x32_bf16 v[76:79], v[154:157], v[236:239], v[76:79]
	v_mfma_f32_16x16x32_bf16 v[120:123], v[158:161], v[208:211], v[120:123]
	v_mfma_f32_16x16x32_bf16 v[116:119], v[180:183], v[208:211], v[116:119]
	v_mfma_f32_16x16x32_bf16 v[104:107], v[158:161], v[216:219], v[104:107]
	v_mfma_f32_16x16x32_bf16 v[100:103], v[180:183], v[216:219], v[100:103]
	v_mfma_f32_16x16x32_bf16 v[88:91], v[158:161], v[224:227], v[88:91]
	v_mfma_f32_16x16x32_bf16 v[84:87], v[180:183], v[224:227], v[84:87]
	v_mfma_f32_16x16x32_bf16 v[72:75], v[158:161], v[232:235], v[72:75]
	v_mfma_f32_16x16x32_bf16 v[68:71], v[180:183], v[232:235], v[68:71]
	v_mfma_f32_16x16x32_bf16 v[120:123], v[174:177], v[212:215], v[120:123]
	v_mfma_f32_16x16x32_bf16 v[116:119], v[204:207], v[212:215], v[116:119]
	v_mfma_f32_16x16x32_bf16 v[104:107], v[174:177], v[220:223], v[104:107]
	v_mfma_f32_16x16x32_bf16 v[100:103], v[204:207], v[220:223], v[100:103]
	v_mfma_f32_16x16x32_bf16 v[88:91], v[174:177], v[228:231], v[88:91]
	v_mfma_f32_16x16x32_bf16 v[84:87], v[204:207], v[228:231], v[84:87]
	v_mfma_f32_16x16x32_bf16 v[72:75], v[174:177], v[236:239], v[72:75]
	v_mfma_f32_16x16x32_bf16 v[68:71], v[204:207], v[236:239], v[68:71]
	s_setprio 3
	s_barrier
	s_add_i32 s37, s37, s54
	s_add_i32 m0, s37, 0xffffff80
	ds_read_b128 v[208:211], v179 offset:49152
	ds_read_b128 v[212:215], v179 offset:50176
	ds_read_b128 v[216:219], v179 offset:51200
	ds_read_b128 v[220:223], v179 offset:52224
	ds_read_b128 v[224:227], v179 offset:53248
	ds_read_b128 v[228:231], v179 offset:54272
	ds_read_b128 v[232:235], v179 offset:55296
	ds_read_b128 v[236:239], v179 offset:56320
	global_load_lds_dwordx4 v2, s[44:45] offset:128
	s_add_i32 m0, s37, 0x1f80
	s_add_u32 s40, s44, 0x80080
	s_addc_u32 s41, s45, 0
	s_add_i32 s37, s39, s54
	global_load_lds_dwordx4 v132, s[44:45] offset:128
	s_mov_b32 m0, s37
	s_nop 0
	global_load_lds_dwordx4 v2, s[40:41]
	s_add_i32 m0, s37, 0x2000
	s_nop 0
	global_load_lds_dwordx4 v132, s[40:41]
	s_add_i32 m0, s60, 0xffffff80
	s_nop 0
	global_load_lds_dwordx4 v2, s[46:47] offset:128
	s_add_i32 m0, s61, 0xffffff80
	s_nop 0
	global_load_lds_dwordx4 v132, s[46:47] offset:128
	s_waitcnt vmcnt(8) lgkmcnt(0)
	s_barrier
	s_setprio 0
	s_waitcnt lgkmcnt(0)
	v_mfma_f32_16x16x32_bf16 v[64:67], v[142:145], v[208:211], v[64:67]
	v_mfma_f32_16x16x32_bf16 v[60:63], v[150:153], v[208:211], v[60:63]
	v_mfma_f32_16x16x32_bf16 v[48:51], v[142:145], v[216:219], v[48:51]
	v_mfma_f32_16x16x32_bf16 v[44:47], v[150:153], v[216:219], v[44:47]
	v_mfma_f32_16x16x32_bf16 v[32:35], v[142:145], v[224:227], v[32:35]
	v_mfma_f32_16x16x32_bf16 v[28:31], v[150:153], v[224:227], v[28:31]
	v_mfma_f32_16x16x32_bf16 v[16:19], v[142:145], v[232:235], v[16:19]
	v_mfma_f32_16x16x32_bf16 v[12:15], v[150:153], v[232:235], v[12:15]
	v_mfma_f32_16x16x32_bf16 v[64:67], v[146:149], v[212:215], v[64:67]
	v_mfma_f32_16x16x32_bf16 v[60:63], v[154:157], v[212:215], v[60:63]
	v_mfma_f32_16x16x32_bf16 v[48:51], v[146:149], v[220:223], v[48:51]
	v_mfma_f32_16x16x32_bf16 v[44:47], v[154:157], v[220:223], v[44:47]
	v_mfma_f32_16x16x32_bf16 v[32:35], v[146:149], v[228:231], v[32:35]
	v_mfma_f32_16x16x32_bf16 v[28:31], v[154:157], v[228:231], v[28:31]
	v_mfma_f32_16x16x32_bf16 v[16:19], v[146:149], v[236:239], v[16:19]
	v_mfma_f32_16x16x32_bf16 v[12:15], v[154:157], v[236:239], v[12:15]
	v_mfma_f32_16x16x32_bf16 v[56:59], v[158:161], v[208:211], v[56:59]
	v_mfma_f32_16x16x32_bf16 v[52:55], v[180:183], v[208:211], v[52:55]
	v_mfma_f32_16x16x32_bf16 v[40:43], v[158:161], v[216:219], v[40:43]
	v_mfma_f32_16x16x32_bf16 v[36:39], v[180:183], v[216:219], v[36:39]
	v_mfma_f32_16x16x32_bf16 v[24:27], v[158:161], v[224:227], v[24:27]
	v_mfma_f32_16x16x32_bf16 v[20:23], v[180:183], v[224:227], v[20:23]
	v_mfma_f32_16x16x32_bf16 v[8:11], v[158:161], v[232:235], v[8:11]
	v_mfma_f32_16x16x32_bf16 v[4:7], v[180:183], v[232:235], v[4:7]
	v_mfma_f32_16x16x32_bf16 v[56:59], v[174:177], v[212:215], v[56:59]
	v_mfma_f32_16x16x32_bf16 v[52:55], v[204:207], v[212:215], v[52:55]
	v_mfma_f32_16x16x32_bf16 v[40:43], v[174:177], v[220:223], v[40:43]
	v_mfma_f32_16x16x32_bf16 v[36:39], v[204:207], v[220:223], v[36:39]
	v_mfma_f32_16x16x32_bf16 v[24:27], v[174:177], v[228:231], v[24:27]
	v_mfma_f32_16x16x32_bf16 v[20:23], v[204:207], v[228:231], v[20:23]
	v_mfma_f32_16x16x32_bf16 v[8:11], v[174:177], v[236:239], v[8:11]
	v_mfma_f32_16x16x32_bf16 v[4:7], v[204:207], v[236:239], v[4:7]
	s_setprio 3
	s_barrier
	s_add_i32 s31, s31, 2
	s_add_u32 s2, s2, 0x100
	s_addc_u32 s29, s29, 0
	s_cmp_gt_u32 s31, 29
	s_mov_b64 s[40:41], s[42:43]
	s_cbranch_scc0 .LBB0_2185
	s_and_b64 vcc, exec, s[26:27]
	s_cbranch_vccz .LBB0_2188
	s_barrier
